# adds: first K-loop iteration of every GEMM peeled with srcC=0 on the first MFMA of each accumulator; the per-tile accumulator zeroing block is gone
# speedup vs baseline: 1.0152x; 1.0033x over previous
; #define PG8_STAGE(bufoff, gbase, voff) do { _Pragma("unroll") for (int _i = 0; _i < 2; ++_i) \
;         __builtin_amdgcn_global_load_lds((const unsigned*)((const char*)(gbase) + (voff)[_i]), (LAS unsigned*)(lds + (bufoff) + ldsw + _i * 8192), 16, 0, 0); } while (0)
; #define PG8_LDA(dst, b, h) do { _Pragma("unroll") for (int m = 0; m < 4; ++m) _Pragma("unroll") for (int k = 0; k < 2; ++k) dst[m][k] = *(const LAS bf16x8*)(lds + PG8_SA(b, h) + aoff + m * 2048 + k * 1024); } while (0)
; #define PG8_LDB(dst, b, h) do { _Pragma("unroll") for (int n = 0; n < 2; ++n) _Pragma("unroll") for (int k = 0; k < 2; ++k) dst[n][k] = *(const LAS bf16x8*)(lds + PG8_SB(b, h) + boff + n * 2048 + k * 1024); } while (0)
; #define PG8_WAIT_V(n) asm volatile("s_waitcnt vmcnt(" #n ")" ::: "memory")
; #define PG8_WAIT_L(n) asm volatile("s_waitcnt lgkmcnt(" #n ")" ::: "memory")
; #define PG8_BAR __builtin_amdgcn_s_barrier()
; #define PG8_SCHED __builtin_amdgcn_sched_barrier(0)
; template <class Epi, class Sched>
; __device__ __forceinline__ void gemm_phase(LAS unsigned char* lds, const Gemm g, const Sched& S, const Epi& E) {
;     ...
;         const bool has_next = S.next(ui + 1, nxt);
;         const char* nA = has_next ? (const char*)g.A + (size_t)nxt.pm * tstepA + (size_t)nxt.pn * apn : cA; const char* nB = has_next ? (const char*)g.Bt + (size_t)nxt.pn * tstepB : cB;
;         for (int t = 0; t < nt; t += 2) {
;             const bool last = (t == nt - 2);
;             const char* a1 = cA + (size_t)(t + 1) * kstep;
;             const char* a2 = last ? nA : cA + (size_t)(t + 2) * kstep; const char* b2 = last ? nB : cB + (size_t)(t + 2) * kstep;
;             const char* a3 = a2 + kstep; const char* b3 = b2 + kstep;
;             PG8_LDB(B0, 0, 0); PG8_LDB(B1, 0, 1); PG8_SCHED; PG8_LDA(At, 0, 0); PG8_STAGE(PG8_SA(1, 1), a1 + hstepA, voffA);
;             PG8_WAIT_V(8); PG8_WAIT_L(0); PG8_BAR; PG8_MMA(0, 0, At, B0); PG8_MMA(0, 1, At, B1); PG8_BAR; PG8_SCHED;
;             PG8_LDA(At, 0, 1); PG8_STAGE(PG8_SB(0, 0), b2, voffB); PG8_STAGE(PG8_SB(0, 1), b2 + hstepB, voffB); PG8_STAGE(PG8_SA(0, 0), a2, voffA);
;     ...
;         for (int a = 0; a < 2; ++a)
; #pragma unroll
;             for (int b = 0; b < 2; ++b)
; #pragma unroll
;                 for (int m = 0; m < 4; ++m)
; #pragma unroll
;                     for (int n = 0; n < 2; ++n) acc[a][b][m][n] = (f32x4){0.f, 0.f, 0.f, 0.f};
.LBB0_95:
	s_ashr_i32 s13, s12, 31
	s_lshl_b64 s[6:7], s[12:13], 19
	s_add_u32 s46, s84, s6
	s_addc_u32 s47, s85, s7
	s_and_b64 s[6:7], s[50:51], exec
	s_cselect_b32 s13, s47, s43
	s_cselect_b32 s57, s46, s42
	s_ashr_i32 s45, s44, 31
	s_lshl_b64 s[6:7], s[44:45], 19
	s_add_u32 s48, s8, s6
	s_addc_u32 s49, s9, s7
	s_and_b64 s[6:7], s[50:51], exec
	s_cselect_b32 s45, s49, s53
	s_cselect_b32 s68, s48, s52
	s_add_u32 s42, s42, 0x40080
	s_addc_u32 s43, s43, 0
	s_add_u32 s52, s52, 0x100
	s_addc_u32 s53, s53, 0
	s_mov_b32 s69, -2
	s_add_u32 s0, s42, 0xfffc0080
	s_addc_u32 s6, s43, -1
	s_add_i32 s26, 0, 0x10000
	s_cmp_eq_u32 s69, 12
	s_cselect_b32 s15, s13, s6
	s_cselect_b32 s14, s57, s0
	v_add_u32_e32 v152, s26, v156
	s_cselect_b32 s7, s45, s53
	s_cselect_b32 s6, s68, s52
	s_add_i32 s0, 0, 0x14000
	ds_read_b128 v[144:147], v152
	ds_read_b128 v[148:151], v152 offset:1024
	ds_read_b128 v[164:167], v152 offset:2048
	ds_read_b128 v[168:171], v152 offset:3072
	v_add_u32_e32 v152, s0, v156
	ds_read_b128 v[172:175], v152
	ds_read_b128 v[190:193], v152 offset:1024
	ds_read_b128 v[196:199], v152 offset:2048
	ds_read_b128 v[200:203], v152 offset:3072
	v_lshl_add_u64 v[152:153], s[42:43], 0, v[140:141]
	s_add_i32 m0, s21, 0xc000
	ds_read_b128 v[204:207], v162
	ds_read_b128 v[208:211], v162 offset:1024
	ds_read_b128 v[212:215], v162 offset:2048
	ds_read_b128 v[216:219], v162 offset:3072
	ds_read_b128 v[220:223], v162 offset:4096
	ds_read_b128 v[224:227], v162 offset:5120
	ds_read_b128 v[228:231], v162 offset:6144
	ds_read_b128 v[232:235], v162 offset:7168
	global_load_lds_dwordx4 v[152:153], off
	v_lshl_add_u64 v[152:153], s[42:43], 0, v[142:143]
	s_add_i32 m0, s21, 0xe000
	s_nop 0
	global_load_lds_dwordx4 v[152:153], off
	s_waitcnt vmcnt(8)
	s_waitcnt lgkmcnt(0)
	s_barrier
	s_waitcnt lgkmcnt(0)
	v_mfma_f32_16x16x32_bf16 v[128:131], v[144:147], v[204:207], 0
	v_mfma_f32_16x16x32_bf16 v[124:127], v[164:167], v[204:207], 0
	v_mfma_f32_16x16x32_bf16 v[120:123], v[144:147], v[212:215], 0
	v_mfma_f32_16x16x32_bf16 v[108:111], v[164:167], v[212:215], 0
	v_mfma_f32_16x16x32_bf16 v[104:107], v[144:147], v[220:223], 0
	v_mfma_f32_16x16x32_bf16 v[92:95], v[164:167], v[220:223], 0
	v_mfma_f32_16x16x32_bf16 v[88:91], v[144:147], v[228:231], 0
	v_mfma_f32_16x16x32_bf16 v[76:79], v[164:167], v[228:231], 0
	v_mfma_f32_16x16x32_bf16 v[128:131], v[148:151], v[208:211], v[128:131]
	v_mfma_f32_16x16x32_bf16 v[124:127], v[168:171], v[208:211], v[124:127]
	v_mfma_f32_16x16x32_bf16 v[120:123], v[148:151], v[216:219], v[120:123]
	v_mfma_f32_16x16x32_bf16 v[108:111], v[168:171], v[216:219], v[108:111]
	v_mfma_f32_16x16x32_bf16 v[104:107], v[148:151], v[224:227], v[104:107]
	v_mfma_f32_16x16x32_bf16 v[92:95], v[168:171], v[224:227], v[92:95]
	v_mfma_f32_16x16x32_bf16 v[88:91], v[148:151], v[232:235], v[88:91]
	v_mfma_f32_16x16x32_bf16 v[76:79], v[168:171], v[232:235], v[76:79]
	v_mfma_f32_16x16x32_bf16 v[116:119], v[172:175], v[204:207], 0
	v_mfma_f32_16x16x32_bf16 v[112:115], v[196:199], v[204:207], 0
	v_mfma_f32_16x16x32_bf16 v[100:103], v[172:175], v[212:215], 0
	v_mfma_f32_16x16x32_bf16 v[96:99], v[196:199], v[212:215], 0
	v_mfma_f32_16x16x32_bf16 v[84:87], v[172:175], v[220:223], 0
	v_mfma_f32_16x16x32_bf16 v[80:83], v[196:199], v[220:223], 0
	v_mfma_f32_16x16x32_bf16 v[72:75], v[172:175], v[228:231], 0
	v_mfma_f32_16x16x32_bf16 v[68:71], v[196:199], v[228:231], 0
	v_mfma_f32_16x16x32_bf16 v[116:119], v[190:193], v[208:211], v[116:119]
	v_mfma_f32_16x16x32_bf16 v[112:115], v[200:203], v[208:211], v[112:115]
	v_mfma_f32_16x16x32_bf16 v[100:103], v[190:193], v[216:219], v[100:103]
	v_mfma_f32_16x16x32_bf16 v[96:99], v[200:203], v[216:219], v[96:99]
	v_mfma_f32_16x16x32_bf16 v[84:87], v[190:193], v[224:227], v[84:87]
	v_mfma_f32_16x16x32_bf16 v[80:83], v[200:203], v[224:227], v[80:83]
	v_mfma_f32_16x16x32_bf16 v[72:75], v[190:193], v[232:235], v[72:75]
	v_mfma_f32_16x16x32_bf16 v[68:71], v[200:203], v[232:235], v[68:71]
	s_barrier
	s_add_i32 s26, s26, s20
	v_lshl_add_u64 v[152:153], s[6:7], 0, v[160:161]
	s_mov_b32 m0, s26
	ds_read_b128 v[204:207], v162 offset:16384
	ds_read_b128 v[208:211], v162 offset:17408
	ds_read_b128 v[212:215], v162 offset:18432
	ds_read_b128 v[216:219], v162 offset:19456
	ds_read_b128 v[220:223], v162 offset:20480
	ds_read_b128 v[224:227], v162 offset:21504
	ds_read_b128 v[228:231], v162 offset:22528
	ds_read_b128 v[232:235], v162 offset:23552
	global_load_lds_dwordx4 v[152:153], off
	s_add_i32 m0, s26, 0x2000
	s_add_u32 s78, s6, 0x40000
	v_lshl_add_u64 v[176:177], s[6:7], 0, v[136:137]
	s_addc_u32 s79, s7, 0
	s_add_i32 s0, s0, s20
	global_load_lds_dwordx4 v[176:177], off
	v_lshl_add_u64 v[236:237], s[78:79], 0, v[160:161]
	s_mov_b32 m0, s0
	v_lshl_add_u64 v[238:239], s[14:15], 0, v[134:135]
	global_load_lds_dwordx4 v[236:237], off
	v_lshl_add_u64 v[236:237], s[78:79], 0, v[136:137]
	s_add_i32 m0, s0, 0x2000
	s_nop 0
	global_load_lds_dwordx4 v[236:237], off
	v_lshl_add_u64 v[236:237], s[14:15], 0, v[132:133]
	s_mov_b32 m0, s21
	s_nop 0
	global_load_lds_dwordx4 v[236:237], off
	s_mov_b32 m0, s24
	s_nop 0
	global_load_lds_dwordx4 v[238:239], off
	s_waitcnt vmcnt(8)
	s_waitcnt lgkmcnt(0)
	s_barrier
; #define PG8_STAGE(bufoff, gbase, voff) do { _Pragma("unroll") for (int _i = 0; _i < 2; ++_i) \
;         __builtin_amdgcn_global_load_lds((const unsigned*)((const char*)(gbase) + (voff)[_i]), (LAS unsigned*)(lds + (bufoff) + ldsw + _i * 8192), 16, 0, 0); } while (0)
; #define PG8_LDA(dst, b, h) do { _Pragma("unroll") for (int m = 0; m < 4; ++m) _Pragma("unroll") for (int k = 0; k < 2; ++k) dst[m][k] = *(const LAS bf16x8*)(lds + PG8_SA(b, h) + aoff + m * 2048 + k * 1024); } while (0)
; #define PG8_LDB(dst, b, h) do { _Pragma("unroll") for (int n = 0; n < 2; ++n) _Pragma("unroll") for (int k = 0; k < 2; ++k) dst[n][k] = *(const LAS bf16x8*)(lds + PG8_SB(b, h) + boff + n * 2048 + k * 1024); } while (0)
; #define PG8_MMA(ai, bj, At, Bt) do { __builtin_amdgcn_s_setprio(1); _Pragma("unroll") for (int m = 0; m < 4; ++m) _Pragma("unroll") for (int n = 0; n < 2; ++n) _Pragma("unroll") for (int k = 0; k < 2; ++k) \
;         acc[ai][bj][m][n] = __builtin_amdgcn_mfma_f32_16x16x32_bf16(Bt[n][k], At[m][k], acc[ai][bj][m][n], 0, 0, 0); __builtin_amdgcn_s_setprio(0); } while (0)
; #define PG8_WAIT_V(n) asm volatile("s_waitcnt vmcnt(" #n ")" ::: "memory")
; #define PG8_WAIT_L(n) asm volatile("s_waitcnt lgkmcnt(" #n ")" ::: "memory")
; #define PG8_BAR __builtin_amdgcn_s_barrier()
; #define PG8_SCHED __builtin_amdgcn_sched_barrier(0)
; template <class Epi, class Sched>
; __device__ __forceinline__ void gemm_phase(LAS unsigned char* lds, const Gemm g, const Sched& S, const Epi& E) {
;     ...
;             PG8_WAIT_V(8); PG8_WAIT_L(0); PG8_BAR; PG8_MMA(1, 0, At, B0); PG8_MMA(1, 1, At, B1); PG8_BAR; PG8_SCHED;
;             PG8_LDB(B0, 1, 0); PG8_LDB(B1, 1, 1); PG8_SCHED; PG8_LDA(At, 1, 0); PG8_STAGE(PG8_SA(0, 1), a2 + hstepA, voffA);
;             PG8_WAIT_V(8); PG8_WAIT_L(0); PG8_BAR; PG8_MMA(0, 0, At, B0); PG8_MMA(0, 1, At, B1); PG8_BAR; PG8_SCHED;
	s_waitcnt lgkmcnt(0)
	v_mfma_f32_16x16x32_bf16 v[64:67], v[144:147], v[204:207], 0
	v_mfma_f32_16x16x32_bf16 v[60:63], v[164:167], v[204:207], 0
	v_mfma_f32_16x16x32_bf16 v[56:59], v[144:147], v[212:215], 0
	v_mfma_f32_16x16x32_bf16 v[44:47], v[164:167], v[212:215], 0
	v_mfma_f32_16x16x32_bf16 v[40:43], v[144:147], v[220:223], 0
	v_mfma_f32_16x16x32_bf16 v[28:31], v[164:167], v[220:223], 0
	v_mfma_f32_16x16x32_bf16 v[24:27], v[144:147], v[228:231], 0
	v_mfma_f32_16x16x32_bf16 v[12:15], v[164:167], v[228:231], 0
	v_mfma_f32_16x16x32_bf16 v[64:67], v[148:151], v[208:211], v[64:67]
	v_mfma_f32_16x16x32_bf16 v[60:63], v[168:171], v[208:211], v[60:63]
	v_mfma_f32_16x16x32_bf16 v[56:59], v[148:151], v[216:219], v[56:59]
	v_mfma_f32_16x16x32_bf16 v[44:47], v[168:171], v[216:219], v[44:47]
	v_mfma_f32_16x16x32_bf16 v[40:43], v[148:151], v[224:227], v[40:43]
	v_mfma_f32_16x16x32_bf16 v[28:31], v[168:171], v[224:227], v[28:31]
	v_mfma_f32_16x16x32_bf16 v[24:27], v[148:151], v[232:235], v[24:27]
	v_mfma_f32_16x16x32_bf16 v[12:15], v[168:171], v[232:235], v[12:15]
	v_mfma_f32_16x16x32_bf16 v[52:55], v[172:175], v[204:207], 0
	v_mfma_f32_16x16x32_bf16 v[48:51], v[196:199], v[204:207], 0
	v_mfma_f32_16x16x32_bf16 v[36:39], v[172:175], v[212:215], 0
	v_mfma_f32_16x16x32_bf16 v[32:35], v[196:199], v[212:215], 0
	v_mfma_f32_16x16x32_bf16 v[20:23], v[172:175], v[220:223], 0
	v_mfma_f32_16x16x32_bf16 v[16:19], v[196:199], v[220:223], 0
	v_mfma_f32_16x16x32_bf16 v[8:11], v[172:175], v[228:231], 0
	v_mfma_f32_16x16x32_bf16 v[4:7], v[196:199], v[228:231], 0
	v_mfma_f32_16x16x32_bf16 v[52:55], v[190:193], v[208:211], v[52:55]
	v_mfma_f32_16x16x32_bf16 v[48:51], v[200:203], v[208:211], v[48:51]
	v_mfma_f32_16x16x32_bf16 v[36:39], v[190:193], v[216:219], v[36:39]
	v_mfma_f32_16x16x32_bf16 v[32:35], v[200:203], v[216:219], v[32:35]
	v_mfma_f32_16x16x32_bf16 v[20:23], v[190:193], v[224:227], v[20:23]
	v_mfma_f32_16x16x32_bf16 v[16:19], v[200:203], v[224:227], v[16:19]
	v_mfma_f32_16x16x32_bf16 v[8:11], v[190:193], v[232:235], v[8:11]
	v_mfma_f32_16x16x32_bf16 v[4:7], v[200:203], v[232:235], v[4:7]
	s_barrier
	s_add_i32 s0, 0, 0x18000
	v_add_u32_e32 v163, s0, v156
	s_add_i32 s26, 0, 0x1c000
	ds_read_b128 v[144:147], v163
	ds_read_b128 v[148:151], v163 offset:1024
	ds_read_b128 v[164:167], v163 offset:2048
	ds_read_b128 v[168:171], v163 offset:3072
	v_add_u32_e32 v163, s26, v156
	ds_read_b128 v[172:175], v163
	ds_read_b128 v[190:193], v163 offset:1024
	ds_read_b128 v[196:199], v163 offset:2048
	ds_read_b128 v[200:203], v163 offset:3072
	s_add_u32 s14, s14, 0x40000
	s_addc_u32 s15, s15, 0
	s_mov_b32 m0, s25
	v_lshl_add_u64 v[240:241], s[14:15], 0, v[132:133]
	ds_read_b128 v[204:207], v162 offset:32768
	ds_read_b128 v[208:211], v162 offset:33792
	ds_read_b128 v[212:215], v162 offset:34816
	ds_read_b128 v[216:219], v162 offset:35840
	ds_read_b128 v[220:223], v162 offset:36864
	ds_read_b128 v[224:227], v162 offset:37888
	ds_read_b128 v[228:231], v162 offset:38912
	ds_read_b128 v[232:235], v162 offset:39936
	global_load_lds_dwordx4 v[240:241], off
	v_lshl_add_u64 v[240:241], s[14:15], 0, v[134:135]
	s_mov_b32 m0, s28
	s_nop 0
	global_load_lds_dwordx4 v[240:241], off
	s_waitcnt vmcnt(8)
	s_waitcnt lgkmcnt(0)
	s_barrier
	s_waitcnt lgkmcnt(0)
	v_mfma_f32_16x16x32_bf16 v[128:131], v[144:147], v[204:207], v[128:131]
	v_mfma_f32_16x16x32_bf16 v[124:127], v[164:167], v[204:207], v[124:127]
	v_mfma_f32_16x16x32_bf16 v[120:123], v[144:147], v[212:215], v[120:123]
	v_mfma_f32_16x16x32_bf16 v[108:111], v[164:167], v[212:215], v[108:111]
	v_mfma_f32_16x16x32_bf16 v[104:107], v[144:147], v[220:223], v[104:107]
	v_mfma_f32_16x16x32_bf16 v[92:95], v[164:167], v[220:223], v[92:95]
	v_mfma_f32_16x16x32_bf16 v[88:91], v[144:147], v[228:231], v[88:91]
	v_mfma_f32_16x16x32_bf16 v[76:79], v[164:167], v[228:231], v[76:79]
	v_mfma_f32_16x16x32_bf16 v[128:131], v[148:151], v[208:211], v[128:131]
	v_mfma_f32_16x16x32_bf16 v[124:127], v[168:171], v[208:211], v[124:127]
	v_mfma_f32_16x16x32_bf16 v[120:123], v[148:151], v[216:219], v[120:123]
	v_mfma_f32_16x16x32_bf16 v[108:111], v[168:171], v[216:219], v[108:111]
	v_mfma_f32_16x16x32_bf16 v[104:107], v[148:151], v[224:227], v[104:107]
	v_mfma_f32_16x16x32_bf16 v[92:95], v[168:171], v[224:227], v[92:95]
	v_mfma_f32_16x16x32_bf16 v[88:91], v[148:151], v[232:235], v[88:91]
	v_mfma_f32_16x16x32_bf16 v[76:79], v[168:171], v[232:235], v[76:79]
	v_mfma_f32_16x16x32_bf16 v[116:119], v[172:175], v[204:207], v[116:119]
	v_mfma_f32_16x16x32_bf16 v[112:115], v[196:199], v[204:207], v[112:115]
	v_mfma_f32_16x16x32_bf16 v[100:103], v[172:175], v[212:215], v[100:103]
	v_mfma_f32_16x16x32_bf16 v[96:99], v[196:199], v[212:215], v[96:99]
	v_mfma_f32_16x16x32_bf16 v[84:87], v[172:175], v[220:223], v[84:87]
	v_mfma_f32_16x16x32_bf16 v[80:83], v[196:199], v[220:223], v[80:83]
	v_mfma_f32_16x16x32_bf16 v[72:75], v[172:175], v[228:231], v[72:75]
	v_mfma_f32_16x16x32_bf16 v[68:71], v[196:199], v[228:231], v[68:71]
	v_mfma_f32_16x16x32_bf16 v[116:119], v[190:193], v[208:211], v[116:119]
	v_mfma_f32_16x16x32_bf16 v[112:115], v[200:203], v[208:211], v[112:115]
	v_mfma_f32_16x16x32_bf16 v[100:103], v[190:193], v[216:219], v[100:103]
	v_mfma_f32_16x16x32_bf16 v[96:99], v[200:203], v[216:219], v[96:99]
	v_mfma_f32_16x16x32_bf16 v[84:87], v[190:193], v[224:227], v[84:87]
	v_mfma_f32_16x16x32_bf16 v[80:83], v[200:203], v[224:227], v[80:83]
	v_mfma_f32_16x16x32_bf16 v[72:75], v[190:193], v[232:235], v[72:75]
	v_mfma_f32_16x16x32_bf16 v[68:71], v[200:203], v[232:235], v[68:71]
	s_barrier
; #define PG8_STAGE(bufoff, gbase, voff) do { _Pragma("unroll") for (int _i = 0; _i < 2; ++_i) \
;         __builtin_amdgcn_global_load_lds((const unsigned*)((const char*)(gbase) + (voff)[_i]), (LAS unsigned*)(lds + (bufoff) + ldsw + _i * 8192), 16, 0, 0); } while (0)
; #define PG8_LDA(dst, b, h) do { _Pragma("unroll") for (int m = 0; m < 4; ++m) _Pragma("unroll") for (int k = 0; k < 2; ++k) dst[m][k] = *(const LAS bf16x8*)(lds + PG8_SA(b, h) + aoff + m * 2048 + k * 1024); } while (0)
; #define PG8_MMA(ai, bj, At, Bt) do { __builtin_amdgcn_s_setprio(1); _Pragma("unroll") for (int m = 0; m < 4; ++m) _Pragma("unroll") for (int n = 0; n < 2; ++n) _Pragma("unroll") for (int k = 0; k < 2; ++k) \
;         acc[ai][bj][m][n] = __builtin_amdgcn_mfma_f32_16x16x32_bf16(Bt[n][k], At[m][k], acc[ai][bj][m][n], 0, 0, 0); __builtin_amdgcn_s_setprio(0); } while (0)
; #define PG8_WAIT_V(n) asm volatile("s_waitcnt vmcnt(" #n ")" ::: "memory")
; #define PG8_WAIT_L(n) asm volatile("s_waitcnt lgkmcnt(" #n ")" ::: "memory")
; #define PG8_BAR __builtin_amdgcn_s_barrier()
; #define PG8_SCHED __builtin_amdgcn_sched_barrier(0)
; template <class Epi, class Sched>
; __device__ __forceinline__ void gemm_phase(LAS unsigned char* lds, const Gemm g, const Sched& S, const Epi& E) {
;     ...
;             PG8_LDA(At, 1, 1); PG8_STAGE(PG8_SB(1, 0), b3, voffB); PG8_STAGE(PG8_SB(1, 1), b3 + hstepB, voffB); PG8_STAGE(PG8_SA(1, 0), a3, voffA);
;             PG8_WAIT_V(8); PG8_WAIT_L(0); PG8_BAR; PG8_MMA(1, 0, At, B0); PG8_MMA(1, 1, At, B1); PG8_BAR; PG8_SCHED;
;         }
	s_add_i32 s0, s0, s20
	v_lshl_add_u64 v[152:153], v[152:153], 0, s[30:31]
	s_mov_b32 m0, s0
	ds_read_b128 v[204:207], v162 offset:49152
	ds_read_b128 v[208:211], v162 offset:50176
	ds_read_b128 v[212:215], v162 offset:51200
	ds_read_b128 v[216:219], v162 offset:52224
	ds_read_b128 v[220:223], v162 offset:53248
	ds_read_b128 v[224:227], v162 offset:54272
	ds_read_b128 v[228:231], v162 offset:55296
	ds_read_b128 v[232:235], v162 offset:56320
	global_load_lds_dwordx4 v[152:153], off
	s_add_i32 m0, s0, 0x2000
	s_add_u32 s6, s6, 0x40080
	v_lshl_add_u64 v[152:153], v[176:177], 0, s[30:31]
	s_addc_u32 s7, s7, 0
	s_add_i32 s0, s26, s20
	global_load_lds_dwordx4 v[152:153], off
	v_lshl_add_u64 v[152:153], s[6:7], 0, v[160:161]
	s_mov_b32 m0, s0
	s_nop 0
	global_load_lds_dwordx4 v[152:153], off
	v_lshl_add_u64 v[152:153], s[6:7], 0, v[136:137]
	s_add_i32 m0, s0, 0x2000
	s_nop 0
	global_load_lds_dwordx4 v[152:153], off
	v_lshl_add_u64 v[152:153], v[236:237], 0, s[30:31]
	s_mov_b32 m0, s33
	s_nop 0
	global_load_lds_dwordx4 v[152:153], off
	v_lshl_add_u64 v[152:153], v[238:239], 0, s[30:31]
	s_mov_b32 m0, s54
	s_nop 0
	global_load_lds_dwordx4 v[152:153], off
	s_waitcnt vmcnt(8)
	s_waitcnt lgkmcnt(0)
	s_barrier
	s_waitcnt lgkmcnt(0)
	v_mfma_f32_16x16x32_bf16 v[64:67], v[144:147], v[204:207], v[64:67]
	v_mfma_f32_16x16x32_bf16 v[60:63], v[164:167], v[204:207], v[60:63]
	v_mfma_f32_16x16x32_bf16 v[56:59], v[144:147], v[212:215], v[56:59]
	v_mfma_f32_16x16x32_bf16 v[44:47], v[164:167], v[212:215], v[44:47]
	v_mfma_f32_16x16x32_bf16 v[40:43], v[144:147], v[220:223], v[40:43]
	v_mfma_f32_16x16x32_bf16 v[28:31], v[164:167], v[220:223], v[28:31]
	v_mfma_f32_16x16x32_bf16 v[24:27], v[144:147], v[228:231], v[24:27]
	v_mfma_f32_16x16x32_bf16 v[12:15], v[164:167], v[228:231], v[12:15]
	v_mfma_f32_16x16x32_bf16 v[64:67], v[148:151], v[208:211], v[64:67]
	v_mfma_f32_16x16x32_bf16 v[60:63], v[168:171], v[208:211], v[60:63]
	v_mfma_f32_16x16x32_bf16 v[56:59], v[148:151], v[216:219], v[56:59]
	v_mfma_f32_16x16x32_bf16 v[44:47], v[168:171], v[216:219], v[44:47]
	v_mfma_f32_16x16x32_bf16 v[40:43], v[148:151], v[224:227], v[40:43]
	v_mfma_f32_16x16x32_bf16 v[28:31], v[168:171], v[224:227], v[28:31]
	v_mfma_f32_16x16x32_bf16 v[24:27], v[148:151], v[232:235], v[24:27]
	v_mfma_f32_16x16x32_bf16 v[12:15], v[168:171], v[232:235], v[12:15]
	v_mfma_f32_16x16x32_bf16 v[52:55], v[172:175], v[204:207], v[52:55]
	v_mfma_f32_16x16x32_bf16 v[48:51], v[196:199], v[204:207], v[48:51]
	v_mfma_f32_16x16x32_bf16 v[36:39], v[172:175], v[212:215], v[36:39]
	v_mfma_f32_16x16x32_bf16 v[32:35], v[196:199], v[212:215], v[32:35]
	v_mfma_f32_16x16x32_bf16 v[20:23], v[172:175], v[220:223], v[20:23]
	v_mfma_f32_16x16x32_bf16 v[16:19], v[196:199], v[220:223], v[16:19]
	v_mfma_f32_16x16x32_bf16 v[8:11], v[172:175], v[228:231], v[8:11]
	v_mfma_f32_16x16x32_bf16 v[4:7], v[196:199], v[228:231], v[4:7]
	v_mfma_f32_16x16x32_bf16 v[52:55], v[190:193], v[208:211], v[52:55]
	v_mfma_f32_16x16x32_bf16 v[48:51], v[200:203], v[208:211], v[48:51]
	v_mfma_f32_16x16x32_bf16 v[36:39], v[190:193], v[216:219], v[36:39]
	v_mfma_f32_16x16x32_bf16 v[32:35], v[200:203], v[216:219], v[32:35]
	v_mfma_f32_16x16x32_bf16 v[20:23], v[190:193], v[224:227], v[20:23]
	v_mfma_f32_16x16x32_bf16 v[16:19], v[200:203], v[224:227], v[16:19]
	v_mfma_f32_16x16x32_bf16 v[8:11], v[190:193], v[232:235], v[8:11]
	v_mfma_f32_16x16x32_bf16 v[4:7], v[200:203], v[232:235], v[4:7]
	s_barrier
	s_add_i32 s69, s69, 2
	s_add_u32 s42, s42, 0x100
	s_addc_u32 s43, s43, 0
	s_add_u32 s52, s52, 0x100
	s_addc_u32 s53, s53, 0
	s_cmp_gt_u32 s69, 13

; #define PG8_STAGE(bufoff, gbase, voff) do { _Pragma("unroll") for (int _i = 0; _i < 2; ++_i) \
;         __builtin_amdgcn_global_load_lds((const unsigned*)((const char*)(gbase) + (voff)[_i]), (LAS unsigned*)(lds + (bufoff) + ldsw + _i * 8192), 16, 0, 0); } while (0)
; #define PG8_LDA(dst, b, h) do { _Pragma("unroll") for (int m = 0; m < 4; ++m) _Pragma("unroll") for (int k = 0; k < 2; ++k) dst[m][k] = *(const LAS bf16x8*)(lds + PG8_SA(b, h) + aoff + m * 2048 + k * 1024); } while (0)
; #define PG8_LDB(dst, b, h) do { _Pragma("unroll") for (int n = 0; n < 2; ++n) _Pragma("unroll") for (int k = 0; k < 2; ++k) dst[n][k] = *(const LAS bf16x8*)(lds + PG8_SB(b, h) + boff + n * 2048 + k * 1024); } while (0)
; #define PG8_WAIT_V(n) asm volatile("s_waitcnt vmcnt(" #n ")" ::: "memory")
; #define PG8_WAIT_L(n) asm volatile("s_waitcnt lgkmcnt(" #n ")" ::: "memory")
; #define PG8_BAR __builtin_amdgcn_s_barrier()
; #define PG8_SCHED __builtin_amdgcn_sched_barrier(0)
; template <class Epi, class Sched>
; __device__ __forceinline__ void gemm_phase(LAS unsigned char* lds, const Gemm g, const Sched& S, const Epi& E) {
;     ...
;         const bool has_next = S.next(ui + 1, nxt);
;         const char* nA = has_next ? (const char*)g.A + (size_t)nxt.pm * tstepA + (size_t)nxt.pn * apn : cA; const char* nB = has_next ? (const char*)g.Bt + (size_t)nxt.pn * tstepB : cB;
;         for (int t = 0; t < nt; t += 2) {
;             const bool last = (t == nt - 2);
;             const char* a1 = cA + (size_t)(t + 1) * kstep;
;             const char* a2 = last ? nA : cA + (size_t)(t + 2) * kstep; const char* b2 = last ? nB : cB + (size_t)(t + 2) * kstep;
;             const char* a3 = a2 + kstep; const char* b3 = b2 + kstep;
;             PG8_LDB(B0, 0, 0); PG8_LDB(B1, 0, 1); PG8_SCHED; PG8_LDA(At, 0, 0); PG8_STAGE(PG8_SA(1, 1), a1 + hstepA, voffA);
;             PG8_WAIT_V(8); PG8_WAIT_L(0); PG8_BAR; PG8_MMA(0, 0, At, B0); PG8_MMA(0, 1, At, B1); PG8_BAR; PG8_SCHED;
;             PG8_LDA(At, 0, 1); PG8_STAGE(PG8_SB(0, 0), b2, voffB); PG8_STAGE(PG8_SB(0, 1), b2 + hstepB, voffB); PG8_STAGE(PG8_SA(0, 0), a2, voffA);
;     ...
;         for (int a = 0; a < 2; ++a)
; #pragma unroll
;             for (int b = 0; b < 2; ++b)
; #pragma unroll
;                 for (int m = 0; m < 4; ++m)
; #pragma unroll
;                     for (int n = 0; n < 2; ++n) acc[a][b][m][n] = (f32x4){0.f, 0.f, 0.f, 0.f};
.LBB0_357:
	s_ashr_i32 s43, s42, 31
	s_lshl_b64 s[6:7], s[42:43], 19
	v_readlane_b32 s14, v253, 21
	v_readlane_b32 s15, v253, 22
	s_add_u32 s46, s14, s6
	s_addc_u32 s47, s15, s7
	s_and_b64 s[6:7], s[44:45], exec
	s_cselect_b32 s9, s47, s53
	s_cselect_b32 s13, s46, s52
	s_ashr_i32 s23, s22, 31
	s_lshl_b64 s[6:7], s[22:23], 19
	s_add_u32 s48, s28, s6
	s_addc_u32 s49, s35, s7
	s_and_b64 s[6:7], s[44:45], exec
	s_cselect_b32 s21, s49, s55
	s_cselect_b32 s23, s48, s54
	s_add_u32 s52, s52, 0x40080
	s_addc_u32 s53, s53, 0
	s_add_u32 s33, s54, 0x100
	s_addc_u32 s43, s55, 0
	s_mov_b32 s54, -2
	s_waitcnt lgkmcnt(0)
	s_add_u32 s0, s52, 0xfffc0080
	s_addc_u32 s6, s53, -1
	s_add_i32 s26, 0, 0x10000
	s_cmp_eq_u32 s54, 12
	s_cselect_b32 s15, s9, s6
	s_cselect_b32 s14, s13, s0
	s_cselect_b32 s7, s21, s43
	s_cselect_b32 s6, s23, s33
	s_add_i32 s0, 0, 0x14000
	v_add_u32_e32 v140, s26, v186
	v_add_u32_e32 v168, s0, v186
	ds_read_b128 v[128:131], v140
	ds_read_b128 v[132:135], v140 offset:1024
	ds_read_b128 v[136:139], v140 offset:2048
	ds_read_b128 v[140:143], v140 offset:3072
	ds_read_b128 v[144:147], v168
	ds_read_b128 v[148:151], v168 offset:1024
	ds_read_b128 v[152:155], v168 offset:2048
	ds_read_b128 v[168:171], v168 offset:3072
	v_lshl_add_u64 v[226:227], s[52:53], 0, v[164:165]
	s_add_i32 m0, s51, 0xc000
	ds_read_b128 v[172:175], v196
	ds_read_b128 v[198:201], v196 offset:1024
	ds_read_b128 v[202:205], v196 offset:2048
	ds_read_b128 v[206:209], v196 offset:3072
	ds_read_b128 v[210:213], v196 offset:4096
	ds_read_b128 v[214:217], v196 offset:5120
	ds_read_b128 v[218:221], v196 offset:6144
	ds_read_b128 v[222:225], v196 offset:7168
	global_load_lds_dwordx4 v[226:227], off
	v_lshl_add_u64 v[226:227], s[52:53], 0, v[166:167]
	s_add_i32 m0, s51, 0xe000
	s_nop 0
	global_load_lds_dwordx4 v[226:227], off
	s_waitcnt vmcnt(8)
	s_waitcnt lgkmcnt(0)
	s_barrier
	s_waitcnt lgkmcnt(0)
	v_mfma_f32_16x16x32_bf16 v[124:127], v[128:131], v[172:175], 0
	v_mfma_f32_16x16x32_bf16 v[120:123], v[136:139], v[172:175], 0
	v_mfma_f32_16x16x32_bf16 v[108:111], v[128:131], v[202:205], 0
	v_mfma_f32_16x16x32_bf16 v[104:107], v[136:139], v[202:205], 0
	v_mfma_f32_16x16x32_bf16 v[92:95], v[128:131], v[210:213], 0
	v_mfma_f32_16x16x32_bf16 v[88:91], v[136:139], v[210:213], 0
	v_mfma_f32_16x16x32_bf16 v[76:79], v[128:131], v[218:221], 0
	v_mfma_f32_16x16x32_bf16 v[72:75], v[136:139], v[218:221], 0
	v_mfma_f32_16x16x32_bf16 v[124:127], v[132:135], v[198:201], v[124:127]
	v_mfma_f32_16x16x32_bf16 v[120:123], v[140:143], v[198:201], v[120:123]
	v_mfma_f32_16x16x32_bf16 v[108:111], v[132:135], v[206:209], v[108:111]
	v_mfma_f32_16x16x32_bf16 v[104:107], v[140:143], v[206:209], v[104:107]
	v_mfma_f32_16x16x32_bf16 v[92:95], v[132:135], v[214:217], v[92:95]
	v_mfma_f32_16x16x32_bf16 v[88:91], v[140:143], v[214:217], v[88:91]
	v_mfma_f32_16x16x32_bf16 v[76:79], v[132:135], v[222:225], v[76:79]
	v_mfma_f32_16x16x32_bf16 v[72:75], v[140:143], v[222:225], v[72:75]
	v_mfma_f32_16x16x32_bf16 v[116:119], v[144:147], v[172:175], 0
	v_mfma_f32_16x16x32_bf16 v[112:115], v[152:155], v[172:175], 0
	v_mfma_f32_16x16x32_bf16 v[100:103], v[144:147], v[202:205], 0
	v_mfma_f32_16x16x32_bf16 v[96:99], v[152:155], v[202:205], 0
	v_mfma_f32_16x16x32_bf16 v[84:87], v[144:147], v[210:213], 0
	v_mfma_f32_16x16x32_bf16 v[80:83], v[152:155], v[210:213], 0
	v_mfma_f32_16x16x32_bf16 v[68:71], v[144:147], v[218:221], 0
	v_mfma_f32_16x16x32_bf16 v[64:67], v[152:155], v[218:221], 0
	v_mfma_f32_16x16x32_bf16 v[116:119], v[148:151], v[198:201], v[116:119]
	v_mfma_f32_16x16x32_bf16 v[112:115], v[168:171], v[198:201], v[112:115]
	v_mfma_f32_16x16x32_bf16 v[100:103], v[148:151], v[206:209], v[100:103]
	v_mfma_f32_16x16x32_bf16 v[96:99], v[168:171], v[206:209], v[96:99]
	v_mfma_f32_16x16x32_bf16 v[84:87], v[148:151], v[214:217], v[84:87]
	v_mfma_f32_16x16x32_bf16 v[80:83], v[168:171], v[214:217], v[80:83]
	v_mfma_f32_16x16x32_bf16 v[68:71], v[148:151], v[222:225], v[68:71]
	v_mfma_f32_16x16x32_bf16 v[64:67], v[168:171], v[222:225], v[64:67]
	s_barrier
	s_add_i32 s26, s26, s20
	v_lshl_add_u64 v[226:227], s[6:7], 0, v[160:161]
	s_mov_b32 m0, s26
	ds_read_b128 v[172:175], v196 offset:16384
	ds_read_b128 v[198:201], v196 offset:17408
	ds_read_b128 v[202:205], v196 offset:18432
	ds_read_b128 v[206:209], v196 offset:19456
	ds_read_b128 v[210:213], v196 offset:20480
	ds_read_b128 v[214:217], v196 offset:21504
	ds_read_b128 v[218:221], v196 offset:22528
	ds_read_b128 v[222:225], v196 offset:23552
	global_load_lds_dwordx4 v[226:227], off
	s_add_i32 m0, s26, 0x2000
	s_add_u32 s78, s6, 0x40000
	v_lshl_add_u64 v[228:229], s[6:7], 0, v[162:163]
	s_addc_u32 s79, s7, 0
	s_add_i32 s0, s0, s20
	global_load_lds_dwordx4 v[228:229], off
	v_lshl_add_u64 v[230:231], s[78:79], 0, v[160:161]
	s_mov_b32 m0, s0
	v_lshl_add_u64 v[232:233], s[14:15], 0, v[158:159]
	global_load_lds_dwordx4 v[230:231], off
	v_lshl_add_u64 v[230:231], s[78:79], 0, v[162:163]
	s_add_i32 m0, s0, 0x2000
	s_nop 0
	global_load_lds_dwordx4 v[230:231], off
	v_lshl_add_u64 v[230:231], s[14:15], 0, v[156:157]
	s_mov_b32 m0, s51
	s_nop 0
	global_load_lds_dwordx4 v[230:231], off
	s_mov_b32 m0, s56
	s_nop 0
	global_load_lds_dwordx4 v[232:233], off
	s_waitcnt vmcnt(8)
	s_waitcnt lgkmcnt(0)
	s_barrier
; #define PG8_STAGE(bufoff, gbase, voff) do { _Pragma("unroll") for (int _i = 0; _i < 2; ++_i) \
;         __builtin_amdgcn_global_load_lds((const unsigned*)((const char*)(gbase) + (voff)[_i]), (LAS unsigned*)(lds + (bufoff) + ldsw + _i * 8192), 16, 0, 0); } while (0)
; #define PG8_LDA(dst, b, h) do { _Pragma("unroll") for (int m = 0; m < 4; ++m) _Pragma("unroll") for (int k = 0; k < 2; ++k) dst[m][k] = *(const LAS bf16x8*)(lds + PG8_SA(b, h) + aoff + m * 2048 + k * 1024); } while (0)
; #define PG8_LDB(dst, b, h) do { _Pragma("unroll") for (int n = 0; n < 2; ++n) _Pragma("unroll") for (int k = 0; k < 2; ++k) dst[n][k] = *(const LAS bf16x8*)(lds + PG8_SB(b, h) + boff + n * 2048 + k * 1024); } while (0)
; #define PG8_MMA(ai, bj, At, Bt) do { __builtin_amdgcn_s_setprio(1); _Pragma("unroll") for (int m = 0; m < 4; ++m) _Pragma("unroll") for (int n = 0; n < 2; ++n) _Pragma("unroll") for (int k = 0; k < 2; ++k) \
;         acc[ai][bj][m][n] = __builtin_amdgcn_mfma_f32_16x16x32_bf16(Bt[n][k], At[m][k], acc[ai][bj][m][n], 0, 0, 0); __builtin_amdgcn_s_setprio(0); } while (0)
; #define PG8_WAIT_V(n) asm volatile("s_waitcnt vmcnt(" #n ")" ::: "memory")
; #define PG8_WAIT_L(n) asm volatile("s_waitcnt lgkmcnt(" #n ")" ::: "memory")
; #define PG8_BAR __builtin_amdgcn_s_barrier()
; #define PG8_SCHED __builtin_amdgcn_sched_barrier(0)
; template <class Epi, class Sched>
; __device__ __forceinline__ void gemm_phase(LAS unsigned char* lds, const Gemm g, const Sched& S, const Epi& E) {
;     ...
;             PG8_WAIT_V(8); PG8_WAIT_L(0); PG8_BAR; PG8_MMA(1, 0, At, B0); PG8_MMA(1, 1, At, B1); PG8_BAR; PG8_SCHED;
;             PG8_LDB(B0, 1, 0); PG8_LDB(B1, 1, 1); PG8_SCHED; PG8_LDA(At, 1, 0); PG8_STAGE(PG8_SA(0, 1), a2 + hstepA, voffA);
;             PG8_WAIT_V(8); PG8_WAIT_L(0); PG8_BAR; PG8_MMA(0, 0, At, B0); PG8_MMA(0, 1, At, B1); PG8_BAR; PG8_SCHED;
	s_waitcnt lgkmcnt(0)
	v_mfma_f32_16x16x32_bf16 v[60:63], v[128:131], v[172:175], 0
	v_mfma_f32_16x16x32_bf16 v[56:59], v[136:139], v[172:175], 0
	v_mfma_f32_16x16x32_bf16 v[44:47], v[128:131], v[202:205], 0
	v_mfma_f32_16x16x32_bf16 v[40:43], v[136:139], v[202:205], 0
	v_mfma_f32_16x16x32_bf16 v[28:31], v[128:131], v[210:213], 0
	v_mfma_f32_16x16x32_bf16 v[24:27], v[136:139], v[210:213], 0
	v_mfma_f32_16x16x32_bf16 v[12:15], v[128:131], v[218:221], 0
	v_mfma_f32_16x16x32_bf16 v[8:11], v[136:139], v[218:221], 0
	v_mfma_f32_16x16x32_bf16 v[60:63], v[132:135], v[198:201], v[60:63]
	v_mfma_f32_16x16x32_bf16 v[56:59], v[140:143], v[198:201], v[56:59]
	v_mfma_f32_16x16x32_bf16 v[44:47], v[132:135], v[206:209], v[44:47]
	v_mfma_f32_16x16x32_bf16 v[40:43], v[140:143], v[206:209], v[40:43]
	v_mfma_f32_16x16x32_bf16 v[28:31], v[132:135], v[214:217], v[28:31]
	v_mfma_f32_16x16x32_bf16 v[24:27], v[140:143], v[214:217], v[24:27]
	v_mfma_f32_16x16x32_bf16 v[12:15], v[132:135], v[222:225], v[12:15]
	v_mfma_f32_16x16x32_bf16 v[8:11], v[140:143], v[222:225], v[8:11]
	v_mfma_f32_16x16x32_bf16 v[52:55], v[144:147], v[172:175], 0
	v_mfma_f32_16x16x32_bf16 v[48:51], v[152:155], v[172:175], 0
	v_mfma_f32_16x16x32_bf16 v[36:39], v[144:147], v[202:205], 0
	v_mfma_f32_16x16x32_bf16 v[32:35], v[152:155], v[202:205], 0
	v_mfma_f32_16x16x32_bf16 v[20:23], v[144:147], v[210:213], 0
	v_mfma_f32_16x16x32_bf16 v[16:19], v[152:155], v[210:213], 0
	v_mfma_f32_16x16x32_bf16 v[4:7], v[144:147], v[218:221], 0
	v_mfma_f32_16x16x32_bf16 v[0:3], v[152:155], v[218:221], 0
	v_mfma_f32_16x16x32_bf16 v[52:55], v[148:151], v[198:201], v[52:55]
	v_mfma_f32_16x16x32_bf16 v[48:51], v[168:171], v[198:201], v[48:51]
	v_mfma_f32_16x16x32_bf16 v[36:39], v[148:151], v[206:209], v[36:39]
	v_mfma_f32_16x16x32_bf16 v[32:35], v[168:171], v[206:209], v[32:35]
	v_mfma_f32_16x16x32_bf16 v[20:23], v[148:151], v[214:217], v[20:23]
	v_mfma_f32_16x16x32_bf16 v[16:19], v[168:171], v[214:217], v[16:19]
	v_mfma_f32_16x16x32_bf16 v[4:7], v[148:151], v[222:225], v[4:7]
	v_mfma_f32_16x16x32_bf16 v[0:3], v[168:171], v[222:225], v[0:3]
	s_barrier
	s_add_i32 s0, 0, 0x18000
	s_add_i32 s26, 0, 0x1c000
	v_add_u32_e32 v140, s0, v186
	v_add_u32_e32 v168, s26, v186
	ds_read_b128 v[128:131], v140
	ds_read_b128 v[132:135], v140 offset:1024
	ds_read_b128 v[136:139], v140 offset:2048
	ds_read_b128 v[140:143], v140 offset:3072
	ds_read_b128 v[144:147], v168
	ds_read_b128 v[148:151], v168 offset:1024
	ds_read_b128 v[152:155], v168 offset:2048
	ds_read_b128 v[168:171], v168 offset:3072
	s_add_u32 s14, s14, 0x40000
	s_addc_u32 s15, s15, 0
	s_mov_b32 m0, s57
	v_lshl_add_u64 v[234:235], s[14:15], 0, v[156:157]
	ds_read_b128 v[172:175], v196 offset:32768
	ds_read_b128 v[198:201], v196 offset:33792
	ds_read_b128 v[202:205], v196 offset:34816
	ds_read_b128 v[206:209], v196 offset:35840
	ds_read_b128 v[210:213], v196 offset:36864
	ds_read_b128 v[214:217], v196 offset:37888
	ds_read_b128 v[218:221], v196 offset:38912
	ds_read_b128 v[222:225], v196 offset:39936
	global_load_lds_dwordx4 v[234:235], off
	v_lshl_add_u64 v[234:235], s[14:15], 0, v[158:159]
	s_mov_b32 m0, s68
	s_nop 0
	global_load_lds_dwordx4 v[234:235], off
	s_waitcnt vmcnt(8)
	s_waitcnt lgkmcnt(0)
	s_barrier
	s_waitcnt lgkmcnt(0)
	v_mfma_f32_16x16x32_bf16 v[124:127], v[128:131], v[172:175], v[124:127]
	v_mfma_f32_16x16x32_bf16 v[120:123], v[136:139], v[172:175], v[120:123]
	v_mfma_f32_16x16x32_bf16 v[108:111], v[128:131], v[202:205], v[108:111]
	v_mfma_f32_16x16x32_bf16 v[104:107], v[136:139], v[202:205], v[104:107]
	v_mfma_f32_16x16x32_bf16 v[92:95], v[128:131], v[210:213], v[92:95]
	v_mfma_f32_16x16x32_bf16 v[88:91], v[136:139], v[210:213], v[88:91]
	v_mfma_f32_16x16x32_bf16 v[76:79], v[128:131], v[218:221], v[76:79]
	v_mfma_f32_16x16x32_bf16 v[72:75], v[136:139], v[218:221], v[72:75]
	v_mfma_f32_16x16x32_bf16 v[124:127], v[132:135], v[198:201], v[124:127]
	v_mfma_f32_16x16x32_bf16 v[120:123], v[140:143], v[198:201], v[120:123]
	v_mfma_f32_16x16x32_bf16 v[108:111], v[132:135], v[206:209], v[108:111]
	v_mfma_f32_16x16x32_bf16 v[104:107], v[140:143], v[206:209], v[104:107]
	v_mfma_f32_16x16x32_bf16 v[92:95], v[132:135], v[214:217], v[92:95]
	v_mfma_f32_16x16x32_bf16 v[88:91], v[140:143], v[214:217], v[88:91]
	v_mfma_f32_16x16x32_bf16 v[76:79], v[132:135], v[222:225], v[76:79]
	v_mfma_f32_16x16x32_bf16 v[72:75], v[140:143], v[222:225], v[72:75]
	v_mfma_f32_16x16x32_bf16 v[116:119], v[144:147], v[172:175], v[116:119]
	v_mfma_f32_16x16x32_bf16 v[112:115], v[152:155], v[172:175], v[112:115]
	v_mfma_f32_16x16x32_bf16 v[100:103], v[144:147], v[202:205], v[100:103]
	v_mfma_f32_16x16x32_bf16 v[96:99], v[152:155], v[202:205], v[96:99]
	v_mfma_f32_16x16x32_bf16 v[84:87], v[144:147], v[210:213], v[84:87]
	v_mfma_f32_16x16x32_bf16 v[80:83], v[152:155], v[210:213], v[80:83]
	v_mfma_f32_16x16x32_bf16 v[68:71], v[144:147], v[218:221], v[68:71]
	v_mfma_f32_16x16x32_bf16 v[64:67], v[152:155], v[218:221], v[64:67]
	v_mfma_f32_16x16x32_bf16 v[116:119], v[148:151], v[198:201], v[116:119]
	v_mfma_f32_16x16x32_bf16 v[112:115], v[168:171], v[198:201], v[112:115]
	v_mfma_f32_16x16x32_bf16 v[100:103], v[148:151], v[206:209], v[100:103]
	v_mfma_f32_16x16x32_bf16 v[96:99], v[168:171], v[206:209], v[96:99]
	v_mfma_f32_16x16x32_bf16 v[84:87], v[148:151], v[214:217], v[84:87]
	v_mfma_f32_16x16x32_bf16 v[80:83], v[168:171], v[214:217], v[80:83]
	v_mfma_f32_16x16x32_bf16 v[68:71], v[148:151], v[222:225], v[68:71]
	v_mfma_f32_16x16x32_bf16 v[64:67], v[168:171], v[222:225], v[64:67]
	s_barrier
; #define PG8_STAGE(bufoff, gbase, voff) do { _Pragma("unroll") for (int _i = 0; _i < 2; ++_i) \
;         __builtin_amdgcn_global_load_lds((const unsigned*)((const char*)(gbase) + (voff)[_i]), (LAS unsigned*)(lds + (bufoff) + ldsw + _i * 8192), 16, 0, 0); } while (0)
; #define PG8_LDA(dst, b, h) do { _Pragma("unroll") for (int m = 0; m < 4; ++m) _Pragma("unroll") for (int k = 0; k < 2; ++k) dst[m][k] = *(const LAS bf16x8*)(lds + PG8_SA(b, h) + aoff + m * 2048 + k * 1024); } while (0)
; #define PG8_MMA(ai, bj, At, Bt) do { __builtin_amdgcn_s_setprio(1); _Pragma("unroll") for (int m = 0; m < 4; ++m) _Pragma("unroll") for (int n = 0; n < 2; ++n) _Pragma("unroll") for (int k = 0; k < 2; ++k) \
;         acc[ai][bj][m][n] = __builtin_amdgcn_mfma_f32_16x16x32_bf16(Bt[n][k], At[m][k], acc[ai][bj][m][n], 0, 0, 0); __builtin_amdgcn_s_setprio(0); } while (0)
; #define PG8_WAIT_V(n) asm volatile("s_waitcnt vmcnt(" #n ")" ::: "memory")
; #define PG8_WAIT_L(n) asm volatile("s_waitcnt lgkmcnt(" #n ")" ::: "memory")
; #define PG8_BAR __builtin_amdgcn_s_barrier()
; #define PG8_SCHED __builtin_amdgcn_sched_barrier(0)
; template <class Epi, class Sched>
; __device__ __forceinline__ void gemm_phase(LAS unsigned char* lds, const Gemm g, const Sched& S, const Epi& E) {
;     ...
;             PG8_LDA(At, 1, 1); PG8_STAGE(PG8_SB(1, 0), b3, voffB); PG8_STAGE(PG8_SB(1, 1), b3 + hstepB, voffB); PG8_STAGE(PG8_SA(1, 0), a3, voffA);
;             PG8_WAIT_V(8); PG8_WAIT_L(0); PG8_BAR; PG8_MMA(1, 0, At, B0); PG8_MMA(1, 1, At, B1); PG8_BAR; PG8_SCHED;
;         }
	s_add_i32 s0, s0, s20
	v_lshl_add_u64 v[226:227], v[226:227], 0, s[30:31]
	s_mov_b32 m0, s0
	ds_read_b128 v[172:175], v196 offset:49152
	ds_read_b128 v[198:201], v196 offset:50176
	ds_read_b128 v[202:205], v196 offset:51200
	ds_read_b128 v[206:209], v196 offset:52224
	ds_read_b128 v[210:213], v196 offset:53248
	ds_read_b128 v[214:217], v196 offset:54272
	ds_read_b128 v[218:221], v196 offset:55296
	ds_read_b128 v[222:225], v196 offset:56320
	global_load_lds_dwordx4 v[226:227], off
	s_add_i32 m0, s0, 0x2000
	s_add_u32 s6, s6, 0x40080
	v_lshl_add_u64 v[226:227], v[228:229], 0, s[30:31]
	s_addc_u32 s7, s7, 0
	s_add_i32 s0, s26, s20
	global_load_lds_dwordx4 v[226:227], off
	v_lshl_add_u64 v[226:227], s[6:7], 0, v[160:161]
	s_mov_b32 m0, s0
	s_nop 0
	global_load_lds_dwordx4 v[226:227], off
	v_lshl_add_u64 v[226:227], s[6:7], 0, v[162:163]
	s_add_i32 m0, s0, 0x2000
	s_nop 0
	global_load_lds_dwordx4 v[226:227], off
	v_lshl_add_u64 v[226:227], v[230:231], 0, s[30:31]
	s_mov_b32 m0, s24
	s_nop 0
	global_load_lds_dwordx4 v[226:227], off
	v_lshl_add_u64 v[226:227], v[232:233], 0, s[30:31]
	s_mov_b32 m0, s25
	s_nop 0
	global_load_lds_dwordx4 v[226:227], off
	s_waitcnt vmcnt(8)
	s_waitcnt lgkmcnt(0)
	s_barrier
	s_waitcnt lgkmcnt(0)
	v_mfma_f32_16x16x32_bf16 v[60:63], v[128:131], v[172:175], v[60:63]
	v_mfma_f32_16x16x32_bf16 v[56:59], v[136:139], v[172:175], v[56:59]
	v_mfma_f32_16x16x32_bf16 v[44:47], v[128:131], v[202:205], v[44:47]
	v_mfma_f32_16x16x32_bf16 v[40:43], v[136:139], v[202:205], v[40:43]
	v_mfma_f32_16x16x32_bf16 v[28:31], v[128:131], v[210:213], v[28:31]
	v_mfma_f32_16x16x32_bf16 v[24:27], v[136:139], v[210:213], v[24:27]
	v_mfma_f32_16x16x32_bf16 v[12:15], v[128:131], v[218:221], v[12:15]
	v_mfma_f32_16x16x32_bf16 v[8:11], v[136:139], v[218:221], v[8:11]
	v_mfma_f32_16x16x32_bf16 v[60:63], v[132:135], v[198:201], v[60:63]
	v_mfma_f32_16x16x32_bf16 v[56:59], v[140:143], v[198:201], v[56:59]
	v_mfma_f32_16x16x32_bf16 v[44:47], v[132:135], v[206:209], v[44:47]
	v_mfma_f32_16x16x32_bf16 v[40:43], v[140:143], v[206:209], v[40:43]
	v_mfma_f32_16x16x32_bf16 v[28:31], v[132:135], v[214:217], v[28:31]
	v_mfma_f32_16x16x32_bf16 v[24:27], v[140:143], v[214:217], v[24:27]
	v_mfma_f32_16x16x32_bf16 v[12:15], v[132:135], v[222:225], v[12:15]
	v_mfma_f32_16x16x32_bf16 v[8:11], v[140:143], v[222:225], v[8:11]
	v_mfma_f32_16x16x32_bf16 v[52:55], v[144:147], v[172:175], v[52:55]
	v_mfma_f32_16x16x32_bf16 v[48:51], v[152:155], v[172:175], v[48:51]
	v_mfma_f32_16x16x32_bf16 v[36:39], v[144:147], v[202:205], v[36:39]
	v_mfma_f32_16x16x32_bf16 v[32:35], v[152:155], v[202:205], v[32:35]
	v_mfma_f32_16x16x32_bf16 v[20:23], v[144:147], v[210:213], v[20:23]
	v_mfma_f32_16x16x32_bf16 v[16:19], v[152:155], v[210:213], v[16:19]
	v_mfma_f32_16x16x32_bf16 v[4:7], v[144:147], v[218:221], v[4:7]
	v_mfma_f32_16x16x32_bf16 v[0:3], v[152:155], v[218:221], v[0:3]
	v_mfma_f32_16x16x32_bf16 v[52:55], v[148:151], v[198:201], v[52:55]
	v_mfma_f32_16x16x32_bf16 v[48:51], v[168:171], v[198:201], v[48:51]
	v_mfma_f32_16x16x32_bf16 v[36:39], v[148:151], v[206:209], v[36:39]
	v_mfma_f32_16x16x32_bf16 v[32:35], v[168:171], v[206:209], v[32:35]
	v_mfma_f32_16x16x32_bf16 v[20:23], v[148:151], v[214:217], v[20:23]
	v_mfma_f32_16x16x32_bf16 v[16:19], v[168:171], v[214:217], v[16:19]
	v_mfma_f32_16x16x32_bf16 v[4:7], v[148:151], v[222:225], v[4:7]
	v_mfma_f32_16x16x32_bf16 v[0:3], v[168:171], v[222:225], v[0:3]
	s_barrier
	s_add_i32 s54, s54, 2
	s_add_u32 s52, s52, 0x100
	s_addc_u32 s53, s53, 0
	s_add_u32 s33, s33, 0x100
	s_addc_u32 s43, s43, 0
	s_cmp_gt_u32 s54, 13

; #define PG8_STAGE(bufoff, gbase, voff) do { _Pragma("unroll") for (int _i = 0; _i < 2; ++_i) \
;         __builtin_amdgcn_global_load_lds((const unsigned*)((const char*)(gbase) + (voff)[_i]), (LAS unsigned*)(lds + (bufoff) + ldsw + _i * 8192), 16, 0, 0); } while (0)
; #define PG8_LDA(dst, b, h) do { _Pragma("unroll") for (int m = 0; m < 4; ++m) _Pragma("unroll") for (int k = 0; k < 2; ++k) dst[m][k] = *(const LAS bf16x8*)(lds + PG8_SA(b, h) + aoff + m * 2048 + k * 1024); } while (0)
; #define PG8_LDB(dst, b, h) do { _Pragma("unroll") for (int n = 0; n < 2; ++n) _Pragma("unroll") for (int k = 0; k < 2; ++k) dst[n][k] = *(const LAS bf16x8*)(lds + PG8_SB(b, h) + boff + n * 2048 + k * 1024); } while (0)
; #define PG8_WAIT_V(n) asm volatile("s_waitcnt vmcnt(" #n ")" ::: "memory")
; #define PG8_WAIT_L(n) asm volatile("s_waitcnt lgkmcnt(" #n ")" ::: "memory")
; #define PG8_BAR __builtin_amdgcn_s_barrier()
; #define PG8_SCHED __builtin_amdgcn_sched_barrier(0)
; template <class Epi, class Sched>
; __device__ __forceinline__ void gemm_phase(LAS unsigned char* lds, const Gemm g, const Sched& S, const Epi& E) {
;     ...
;         const bool has_next = S.next(ui + 1, nxt);
;         const char* nA = has_next ? (const char*)g.A + (size_t)nxt.pm * tstepA + (size_t)nxt.pn * apn : cA; const char* nB = has_next ? (const char*)g.Bt + (size_t)nxt.pn * tstepB : cB;
;         for (int t = 0; t < nt; t += 2) {
;             const bool last = (t == nt - 2);
;             const char* a1 = cA + (size_t)(t + 1) * kstep;
;             const char* a2 = last ? nA : cA + (size_t)(t + 2) * kstep; const char* b2 = last ? nB : cB + (size_t)(t + 2) * kstep;
;             const char* a3 = a2 + kstep; const char* b3 = b2 + kstep;
;             PG8_LDB(B0, 0, 0); PG8_LDB(B1, 0, 1); PG8_SCHED; PG8_LDA(At, 0, 0); PG8_STAGE(PG8_SA(1, 1), a1 + hstepA, voffA);
;             PG8_WAIT_V(8); PG8_WAIT_L(0); PG8_BAR; PG8_MMA(0, 0, At, B0); PG8_MMA(0, 1, At, B1); PG8_BAR; PG8_SCHED;
;             PG8_LDA(At, 0, 1); PG8_STAGE(PG8_SB(0, 0), b2, voffB); PG8_STAGE(PG8_SB(0, 1), b2 + hstepB, voffB); PG8_STAGE(PG8_SA(0, 0), a2, voffA);
;     ...
;         for (int a = 0; a < 2; ++a)
; #pragma unroll
;             for (int b = 0; b < 2; ++b)
; #pragma unroll
;                 for (int m = 0; m < 4; ++m)
; #pragma unroll
;                     for (int n = 0; n < 2; ++n) acc[a][b][m][n] = (f32x4){0.f, 0.f, 0.f, 0.f};
.LBB0_627:
	s_lshl_b64 s[6:7], s[22:23], 17
	s_add_u32 s46, s28, s6
	s_addc_u32 s47, s20, s7
	s_and_b64 s[6:7], exec, s[42:43]
	s_cselect_b32 s9, s47, s51
	s_cselect_b32 s13, s46, s50
	s_mov_b32 s6, 0
	s_mov_b64 s[54:55], -1
	s_mov_b64 s[56:57], 0
	s_waitcnt lgkmcnt(0)
	s_add_u32 s0, s52, s6
	s_addc_u32 s23, s53, 0
	s_add_u32 s7, s0, 0x100
	s_addc_u32 s26, s23, 0
	s_and_b64 s[14:15], s[56:57], exec
	s_cselect_b32 vcc_hi, s45, s26
	s_cselect_b32 vcc_lo, s44, s7
	s_add_u32 s6, s50, s6
	s_addc_u32 s7, s51, 0
	s_add_u32 s14, s6, 0x100
	s_addc_u32 s15, s7, 0
	s_add_i32 s80, 0, 0x10000
	s_and_b64 s[6:7], s[56:57], exec
	s_cselect_b32 s7, s9, s15
	s_cselect_b32 s6, s13, s14
	s_add_i32 s57, 0, 0x14000
	s_add_u32 s78, s0, 0x40080
	s_addc_u32 s79, s23, 0
	s_add_i32 s97, s80, s24
	s_add_i32 m0, s25, 0xc000
	s_add_i32 s81, s25, 0xe000
	s_add_i32 s88, s97, 0x2000
	s_add_u32 s14, s6, 0x10000
	v_add_u32_e32 v140, s80, v174
	v_add_u32_e32 v164, s57, v174
	s_addc_u32 s15, s7, 0
	s_add_i32 s89, s57, s24
	ds_read_b128 v[128:131], v140
	ds_read_b128 v[132:135], v140 offset:1024
	ds_read_b128 v[136:139], v140 offset:2048
	ds_read_b128 v[140:143], v140 offset:3072
	ds_read_b128 v[144:147], v164
	ds_read_b128 v[148:151], v164 offset:1024
	ds_read_b128 v[152:155], v164 offset:2048
	ds_read_b128 v[164:167], v164 offset:3072
	s_add_i32 s96, s89, 0x2000
	s_add_i32 s35, 0, 0x18000
	s_add_i32 s0, 0, 0x1c000
	s_add_u32 s68, vcc_lo, 0x40000
	s_addc_u32 s69, vcc_hi, 0
	s_add_i32 s23, s35, s24
	s_add_i32 s26, s23, 0x2000
	s_add_u32 s56, s6, 0x10080
	s_addc_u32 s57, s7, 0
	s_add_i32 s83, s0, s24
	s_add_i32 s80, s83, 0x2000
	v_lshl_add_u64 v[192:193], s[78:79], 0, v[156:157]
	ds_read_b128 v[168:171], v191
	ds_read_b128 v[196:199], v191 offset:1024
	ds_read_b128 v[200:203], v191 offset:2048
	ds_read_b128 v[204:207], v191 offset:3072
	ds_read_b128 v[208:211], v191 offset:4096
	ds_read_b128 v[212:215], v191 offset:5120
	ds_read_b128 v[216:219], v191 offset:6144
	ds_read_b128 v[220:223], v191 offset:7168
	global_load_lds_dwordx4 v[192:193], off
	v_lshl_add_u64 v[192:193], s[78:79], 0, v[158:159]
	s_mov_b32 m0, s81
	s_nop 0
	global_load_lds_dwordx4 v[192:193], off
	s_waitcnt vmcnt(8)
	s_waitcnt lgkmcnt(0)
	s_barrier
	s_waitcnt lgkmcnt(0)
	v_mfma_f32_16x16x32_bf16 v[124:127], v[128:131], v[168:171], 0
	v_mfma_f32_16x16x32_bf16 v[120:123], v[136:139], v[168:171], 0
	v_mfma_f32_16x16x32_bf16 v[108:111], v[128:131], v[200:203], 0
	v_mfma_f32_16x16x32_bf16 v[104:107], v[136:139], v[200:203], 0
	v_mfma_f32_16x16x32_bf16 v[92:95], v[128:131], v[208:211], 0
	v_mfma_f32_16x16x32_bf16 v[88:91], v[136:139], v[208:211], 0
	v_mfma_f32_16x16x32_bf16 v[76:79], v[128:131], v[216:219], 0
	v_mfma_f32_16x16x32_bf16 v[72:75], v[136:139], v[216:219], 0
	v_mfma_f32_16x16x32_bf16 v[124:127], v[132:135], v[196:199], v[124:127]
	v_mfma_f32_16x16x32_bf16 v[120:123], v[140:143], v[196:199], v[120:123]
	v_mfma_f32_16x16x32_bf16 v[108:111], v[132:135], v[204:207], v[108:111]
	v_mfma_f32_16x16x32_bf16 v[104:107], v[140:143], v[204:207], v[104:107]
	v_mfma_f32_16x16x32_bf16 v[92:95], v[132:135], v[212:215], v[92:95]
	v_mfma_f32_16x16x32_bf16 v[88:91], v[140:143], v[212:215], v[88:91]
	v_mfma_f32_16x16x32_bf16 v[76:79], v[132:135], v[220:223], v[76:79]
	v_mfma_f32_16x16x32_bf16 v[72:75], v[140:143], v[220:223], v[72:75]
	v_mfma_f32_16x16x32_bf16 v[116:119], v[144:147], v[168:171], 0
	v_mfma_f32_16x16x32_bf16 v[112:115], v[152:155], v[168:171], 0
	v_mfma_f32_16x16x32_bf16 v[100:103], v[144:147], v[200:203], 0
	v_mfma_f32_16x16x32_bf16 v[96:99], v[152:155], v[200:203], 0
	v_mfma_f32_16x16x32_bf16 v[84:87], v[144:147], v[208:211], 0
	v_mfma_f32_16x16x32_bf16 v[80:83], v[152:155], v[208:211], 0
	v_mfma_f32_16x16x32_bf16 v[68:71], v[144:147], v[216:219], 0
	v_mfma_f32_16x16x32_bf16 v[64:67], v[152:155], v[216:219], 0
	v_mfma_f32_16x16x32_bf16 v[116:119], v[148:151], v[196:199], v[116:119]
	v_mfma_f32_16x16x32_bf16 v[112:115], v[164:167], v[196:199], v[112:115]
	v_mfma_f32_16x16x32_bf16 v[100:103], v[148:151], v[204:207], v[100:103]
	v_mfma_f32_16x16x32_bf16 v[96:99], v[164:167], v[204:207], v[96:99]
	v_mfma_f32_16x16x32_bf16 v[84:87], v[148:151], v[212:215], v[84:87]
	v_mfma_f32_16x16x32_bf16 v[80:83], v[164:167], v[212:215], v[80:83]
	v_mfma_f32_16x16x32_bf16 v[68:71], v[148:151], v[220:223], v[68:71]
	v_mfma_f32_16x16x32_bf16 v[64:67], v[164:167], v[220:223], v[64:67]
	s_barrier
	s_mov_b32 m0, s97
	v_lshl_add_u64 v[192:193], s[6:7], 0, v[160:161]
	ds_read_b128 v[168:171], v191 offset:16384
	ds_read_b128 v[196:199], v191 offset:17408
	ds_read_b128 v[200:203], v191 offset:18432
	ds_read_b128 v[204:207], v191 offset:19456
	ds_read_b128 v[208:211], v191 offset:20480
	ds_read_b128 v[212:215], v191 offset:21504
	ds_read_b128 v[216:219], v191 offset:22528
	ds_read_b128 v[220:223], v191 offset:23552
	global_load_lds_dwordx4 v[192:193], off
	v_lshl_add_u64 v[224:225], s[6:7], 0, v[162:163]
	s_mov_b32 m0, s88
	v_lshl_add_u64 v[226:227], s[14:15], 0, v[160:161]
	global_load_lds_dwordx4 v[224:225], off
	s_mov_b32 m0, s89
	v_lshl_add_u64 v[228:229], vcc, 0, v[158:159]
	global_load_lds_dwordx4 v[226:227], off
	v_lshl_add_u64 v[226:227], s[14:15], 0, v[162:163]
	s_mov_b32 m0, s96
	s_nop 0
	global_load_lds_dwordx4 v[226:227], off
	v_lshl_add_u64 v[226:227], vcc, 0, v[156:157]
	s_mov_b32 m0, s25
	s_nop 0
	global_load_lds_dwordx4 v[226:227], off
	s_mov_b32 m0, s49
	s_nop 0
	global_load_lds_dwordx4 v[228:229], off
	s_waitcnt vmcnt(8)
	s_waitcnt lgkmcnt(0)
	s_barrier
; #define PG8_STAGE(bufoff, gbase, voff) do { _Pragma("unroll") for (int _i = 0; _i < 2; ++_i) \
;         __builtin_amdgcn_global_load_lds((const unsigned*)((const char*)(gbase) + (voff)[_i]), (LAS unsigned*)(lds + (bufoff) + ldsw + _i * 8192), 16, 0, 0); } while (0)
; #define PG8_LDA(dst, b, h) do { _Pragma("unroll") for (int m = 0; m < 4; ++m) _Pragma("unroll") for (int k = 0; k < 2; ++k) dst[m][k] = *(const LAS bf16x8*)(lds + PG8_SA(b, h) + aoff + m * 2048 + k * 1024); } while (0)
; #define PG8_LDB(dst, b, h) do { _Pragma("unroll") for (int n = 0; n < 2; ++n) _Pragma("unroll") for (int k = 0; k < 2; ++k) dst[n][k] = *(const LAS bf16x8*)(lds + PG8_SB(b, h) + boff + n * 2048 + k * 1024); } while (0)
; #define PG8_MMA(ai, bj, At, Bt) do { __builtin_amdgcn_s_setprio(1); _Pragma("unroll") for (int m = 0; m < 4; ++m) _Pragma("unroll") for (int n = 0; n < 2; ++n) _Pragma("unroll") for (int k = 0; k < 2; ++k) \
;         acc[ai][bj][m][n] = __builtin_amdgcn_mfma_f32_16x16x32_bf16(Bt[n][k], At[m][k], acc[ai][bj][m][n], 0, 0, 0); __builtin_amdgcn_s_setprio(0); } while (0)
; #define PG8_WAIT_V(n) asm volatile("s_waitcnt vmcnt(" #n ")" ::: "memory")
; #define PG8_WAIT_L(n) asm volatile("s_waitcnt lgkmcnt(" #n ")" ::: "memory")
; #define PG8_BAR __builtin_amdgcn_s_barrier()
; #define PG8_SCHED __builtin_amdgcn_sched_barrier(0)
; template <class Epi, class Sched>
; __device__ __forceinline__ void gemm_phase(LAS unsigned char* lds, const Gemm g, const Sched& S, const Epi& E) {
;     ...
;             PG8_WAIT_V(8); PG8_WAIT_L(0); PG8_BAR; PG8_MMA(1, 0, At, B0); PG8_MMA(1, 1, At, B1); PG8_BAR; PG8_SCHED;
;             PG8_LDB(B0, 1, 0); PG8_LDB(B1, 1, 1); PG8_SCHED; PG8_LDA(At, 1, 0); PG8_STAGE(PG8_SA(0, 1), a2 + hstepA, voffA);
;             PG8_WAIT_V(8); PG8_WAIT_L(0); PG8_BAR; PG8_MMA(0, 0, At, B0); PG8_MMA(0, 1, At, B1); PG8_BAR; PG8_SCHED;
	s_waitcnt lgkmcnt(0)
	v_mfma_f32_16x16x32_bf16 v[60:63], v[128:131], v[168:171], 0
	v_mfma_f32_16x16x32_bf16 v[56:59], v[136:139], v[168:171], 0
	v_mfma_f32_16x16x32_bf16 v[44:47], v[128:131], v[200:203], 0
	v_mfma_f32_16x16x32_bf16 v[40:43], v[136:139], v[200:203], 0
	v_mfma_f32_16x16x32_bf16 v[28:31], v[128:131], v[208:211], 0
	v_mfma_f32_16x16x32_bf16 v[24:27], v[136:139], v[208:211], 0
	v_mfma_f32_16x16x32_bf16 v[12:15], v[128:131], v[216:219], 0
	v_mfma_f32_16x16x32_bf16 v[8:11], v[136:139], v[216:219], 0
	v_mfma_f32_16x16x32_bf16 v[60:63], v[132:135], v[196:199], v[60:63]
	v_mfma_f32_16x16x32_bf16 v[56:59], v[140:143], v[196:199], v[56:59]
	v_mfma_f32_16x16x32_bf16 v[44:47], v[132:135], v[204:207], v[44:47]
	v_mfma_f32_16x16x32_bf16 v[40:43], v[140:143], v[204:207], v[40:43]
	v_mfma_f32_16x16x32_bf16 v[28:31], v[132:135], v[212:215], v[28:31]
	v_mfma_f32_16x16x32_bf16 v[24:27], v[140:143], v[212:215], v[24:27]
	v_mfma_f32_16x16x32_bf16 v[12:15], v[132:135], v[220:223], v[12:15]
	v_mfma_f32_16x16x32_bf16 v[8:11], v[140:143], v[220:223], v[8:11]
	v_mfma_f32_16x16x32_bf16 v[52:55], v[144:147], v[168:171], 0
	v_mfma_f32_16x16x32_bf16 v[48:51], v[152:155], v[168:171], 0
	v_mfma_f32_16x16x32_bf16 v[36:39], v[144:147], v[200:203], 0
	v_mfma_f32_16x16x32_bf16 v[32:35], v[152:155], v[200:203], 0
	v_mfma_f32_16x16x32_bf16 v[20:23], v[144:147], v[208:211], 0
	v_mfma_f32_16x16x32_bf16 v[16:19], v[152:155], v[208:211], 0
	v_mfma_f32_16x16x32_bf16 v[4:7], v[144:147], v[216:219], 0
	v_mfma_f32_16x16x32_bf16 v[0:3], v[152:155], v[216:219], 0
	v_mfma_f32_16x16x32_bf16 v[52:55], v[148:151], v[196:199], v[52:55]
	v_mfma_f32_16x16x32_bf16 v[48:51], v[164:167], v[196:199], v[48:51]
	v_mfma_f32_16x16x32_bf16 v[36:39], v[148:151], v[204:207], v[36:39]
	v_mfma_f32_16x16x32_bf16 v[32:35], v[164:167], v[204:207], v[32:35]
	v_mfma_f32_16x16x32_bf16 v[20:23], v[148:151], v[212:215], v[20:23]
	v_mfma_f32_16x16x32_bf16 v[16:19], v[164:167], v[212:215], v[16:19]
	v_mfma_f32_16x16x32_bf16 v[4:7], v[148:151], v[220:223], v[4:7]
	v_mfma_f32_16x16x32_bf16 v[0:3], v[164:167], v[220:223], v[0:3]
	s_barrier
	v_add_u32_e32 v140, s35, v174
	v_add_u32_e32 v164, s0, v174
	ds_read_b128 v[128:131], v140
	ds_read_b128 v[132:135], v140 offset:1024
	ds_read_b128 v[136:139], v140 offset:2048
	ds_read_b128 v[140:143], v140 offset:3072
	ds_read_b128 v[144:147], v164
	ds_read_b128 v[148:151], v164 offset:1024
	ds_read_b128 v[152:155], v164 offset:2048
	ds_read_b128 v[164:167], v164 offset:3072
	s_mov_b32 m0, s82
	v_lshl_add_u64 v[230:231], s[68:69], 0, v[156:157]
	ds_read_b128 v[168:171], v191 offset:32768
	ds_read_b128 v[196:199], v191 offset:33792
	ds_read_b128 v[200:203], v191 offset:34816
	ds_read_b128 v[204:207], v191 offset:35840
	ds_read_b128 v[208:211], v191 offset:36864
	ds_read_b128 v[212:215], v191 offset:37888
	ds_read_b128 v[216:219], v191 offset:38912
	ds_read_b128 v[220:223], v191 offset:39936
	global_load_lds_dwordx4 v[230:231], off
	v_lshl_add_u64 v[230:231], s[68:69], 0, v[158:159]
	s_mov_b32 m0, s33
	s_nop 0
	global_load_lds_dwordx4 v[230:231], off
	s_waitcnt vmcnt(8)
	s_waitcnt lgkmcnt(0)
	s_barrier
	s_waitcnt lgkmcnt(0)
	v_mfma_f32_16x16x32_bf16 v[124:127], v[128:131], v[168:171], v[124:127]
	v_mfma_f32_16x16x32_bf16 v[120:123], v[136:139], v[168:171], v[120:123]
	v_mfma_f32_16x16x32_bf16 v[108:111], v[128:131], v[200:203], v[108:111]
	v_mfma_f32_16x16x32_bf16 v[104:107], v[136:139], v[200:203], v[104:107]
	v_mfma_f32_16x16x32_bf16 v[92:95], v[128:131], v[208:211], v[92:95]
	v_mfma_f32_16x16x32_bf16 v[88:91], v[136:139], v[208:211], v[88:91]
	v_mfma_f32_16x16x32_bf16 v[76:79], v[128:131], v[216:219], v[76:79]
	v_mfma_f32_16x16x32_bf16 v[72:75], v[136:139], v[216:219], v[72:75]
	v_mfma_f32_16x16x32_bf16 v[124:127], v[132:135], v[196:199], v[124:127]
	v_mfma_f32_16x16x32_bf16 v[120:123], v[140:143], v[196:199], v[120:123]
	v_mfma_f32_16x16x32_bf16 v[108:111], v[132:135], v[204:207], v[108:111]
	v_mfma_f32_16x16x32_bf16 v[104:107], v[140:143], v[204:207], v[104:107]
	v_mfma_f32_16x16x32_bf16 v[92:95], v[132:135], v[212:215], v[92:95]
	v_mfma_f32_16x16x32_bf16 v[88:91], v[140:143], v[212:215], v[88:91]
	v_mfma_f32_16x16x32_bf16 v[76:79], v[132:135], v[220:223], v[76:79]
	v_mfma_f32_16x16x32_bf16 v[72:75], v[140:143], v[220:223], v[72:75]
	v_mfma_f32_16x16x32_bf16 v[116:119], v[144:147], v[168:171], v[116:119]
	v_mfma_f32_16x16x32_bf16 v[112:115], v[152:155], v[168:171], v[112:115]
	v_mfma_f32_16x16x32_bf16 v[100:103], v[144:147], v[200:203], v[100:103]
	v_mfma_f32_16x16x32_bf16 v[96:99], v[152:155], v[200:203], v[96:99]
	v_mfma_f32_16x16x32_bf16 v[84:87], v[144:147], v[208:211], v[84:87]
	v_mfma_f32_16x16x32_bf16 v[80:83], v[152:155], v[208:211], v[80:83]
	v_mfma_f32_16x16x32_bf16 v[68:71], v[144:147], v[216:219], v[68:71]
	v_mfma_f32_16x16x32_bf16 v[64:67], v[152:155], v[216:219], v[64:67]
	v_mfma_f32_16x16x32_bf16 v[116:119], v[148:151], v[196:199], v[116:119]
	v_mfma_f32_16x16x32_bf16 v[112:115], v[164:167], v[196:199], v[112:115]
	v_mfma_f32_16x16x32_bf16 v[100:103], v[148:151], v[204:207], v[100:103]
	v_mfma_f32_16x16x32_bf16 v[96:99], v[164:167], v[204:207], v[96:99]
	v_mfma_f32_16x16x32_bf16 v[84:87], v[148:151], v[212:215], v[84:87]
	v_mfma_f32_16x16x32_bf16 v[80:83], v[164:167], v[212:215], v[80:83]
	v_mfma_f32_16x16x32_bf16 v[68:71], v[148:151], v[220:223], v[68:71]
	v_mfma_f32_16x16x32_bf16 v[64:67], v[164:167], v[220:223], v[64:67]
	s_barrier
; #define PG8_STAGE(bufoff, gbase, voff) do { _Pragma("unroll") for (int _i = 0; _i < 2; ++_i) \
;         __builtin_amdgcn_global_load_lds((const unsigned*)((const char*)(gbase) + (voff)[_i]), (LAS unsigned*)(lds + (bufoff) + ldsw + _i * 8192), 16, 0, 0); } while (0)
; #define PG8_LDA(dst, b, h) do { _Pragma("unroll") for (int m = 0; m < 4; ++m) _Pragma("unroll") for (int k = 0; k < 2; ++k) dst[m][k] = *(const LAS bf16x8*)(lds + PG8_SA(b, h) + aoff + m * 2048 + k * 1024); } while (0)
; #define PG8_MMA(ai, bj, At, Bt) do { __builtin_amdgcn_s_setprio(1); _Pragma("unroll") for (int m = 0; m < 4; ++m) _Pragma("unroll") for (int n = 0; n < 2; ++n) _Pragma("unroll") for (int k = 0; k < 2; ++k) \
;         acc[ai][bj][m][n] = __builtin_amdgcn_mfma_f32_16x16x32_bf16(Bt[n][k], At[m][k], acc[ai][bj][m][n], 0, 0, 0); __builtin_amdgcn_s_setprio(0); } while (0)
; #define PG8_WAIT_V(n) asm volatile("s_waitcnt vmcnt(" #n ")" ::: "memory")
; #define PG8_WAIT_L(n) asm volatile("s_waitcnt lgkmcnt(" #n ")" ::: "memory")
; #define PG8_BAR __builtin_amdgcn_s_barrier()
; #define PG8_SCHED __builtin_amdgcn_sched_barrier(0)
; template <class Epi, class Sched>
; __device__ __forceinline__ void gemm_phase(LAS unsigned char* lds, const Gemm g, const Sched& S, const Epi& E) {
;     ...
;             PG8_LDA(At, 1, 1); PG8_STAGE(PG8_SB(1, 0), b3, voffB); PG8_STAGE(PG8_SB(1, 1), b3 + hstepB, voffB); PG8_STAGE(PG8_SA(1, 0), a3, voffA);
;             PG8_WAIT_V(8); PG8_WAIT_L(0); PG8_BAR; PG8_MMA(1, 0, At, B0); PG8_MMA(1, 1, At, B1); PG8_BAR; PG8_SCHED;
;         }
	s_mov_b32 m0, s23
	v_lshl_add_u64 v[192:193], v[192:193], 0, s[30:31]
	ds_read_b128 v[168:171], v191 offset:49152
	ds_read_b128 v[196:199], v191 offset:50176
	ds_read_b128 v[200:203], v191 offset:51200
	ds_read_b128 v[204:207], v191 offset:52224
	ds_read_b128 v[208:211], v191 offset:53248
	ds_read_b128 v[212:215], v191 offset:54272
	ds_read_b128 v[216:219], v191 offset:55296
	ds_read_b128 v[220:223], v191 offset:56320
	global_load_lds_dwordx4 v[192:193], off
	v_lshl_add_u64 v[192:193], v[224:225], 0, s[30:31]
	s_mov_b32 m0, s26
	s_nop 0
	global_load_lds_dwordx4 v[192:193], off
	v_lshl_add_u64 v[192:193], s[56:57], 0, v[160:161]
	s_mov_b32 m0, s83
	s_nop 0
	global_load_lds_dwordx4 v[192:193], off
	v_lshl_add_u64 v[192:193], s[56:57], 0, v[162:163]
	s_mov_b32 m0, s80
	s_nop 0
	global_load_lds_dwordx4 v[192:193], off
	v_lshl_add_u64 v[192:193], v[226:227], 0, s[30:31]
	s_mov_b32 m0, s90
	s_nop 0
	global_load_lds_dwordx4 v[192:193], off
	v_lshl_add_u64 v[192:193], v[228:229], 0, s[30:31]
	s_mov_b32 m0, s21
	s_nop 0
	global_load_lds_dwordx4 v[192:193], off
	s_waitcnt vmcnt(8)
	s_waitcnt lgkmcnt(0)
	s_barrier
	s_waitcnt lgkmcnt(0)
	v_mfma_f32_16x16x32_bf16 v[60:63], v[128:131], v[168:171], v[60:63]
	v_mfma_f32_16x16x32_bf16 v[56:59], v[136:139], v[168:171], v[56:59]
	v_mfma_f32_16x16x32_bf16 v[44:47], v[128:131], v[200:203], v[44:47]
	v_mfma_f32_16x16x32_bf16 v[40:43], v[136:139], v[200:203], v[40:43]
	v_mfma_f32_16x16x32_bf16 v[28:31], v[128:131], v[208:211], v[28:31]
	v_mfma_f32_16x16x32_bf16 v[24:27], v[136:139], v[208:211], v[24:27]
	v_mfma_f32_16x16x32_bf16 v[12:15], v[128:131], v[216:219], v[12:15]
	v_mfma_f32_16x16x32_bf16 v[8:11], v[136:139], v[216:219], v[8:11]
	v_mfma_f32_16x16x32_bf16 v[60:63], v[132:135], v[196:199], v[60:63]
	v_mfma_f32_16x16x32_bf16 v[56:59], v[140:143], v[196:199], v[56:59]
	v_mfma_f32_16x16x32_bf16 v[44:47], v[132:135], v[204:207], v[44:47]
	v_mfma_f32_16x16x32_bf16 v[40:43], v[140:143], v[204:207], v[40:43]
	v_mfma_f32_16x16x32_bf16 v[28:31], v[132:135], v[212:215], v[28:31]
	v_mfma_f32_16x16x32_bf16 v[24:27], v[140:143], v[212:215], v[24:27]
	v_mfma_f32_16x16x32_bf16 v[12:15], v[132:135], v[220:223], v[12:15]
	v_mfma_f32_16x16x32_bf16 v[8:11], v[140:143], v[220:223], v[8:11]
	v_mfma_f32_16x16x32_bf16 v[52:55], v[144:147], v[168:171], v[52:55]
	v_mfma_f32_16x16x32_bf16 v[48:51], v[152:155], v[168:171], v[48:51]
	v_mfma_f32_16x16x32_bf16 v[36:39], v[144:147], v[200:203], v[36:39]
	v_mfma_f32_16x16x32_bf16 v[32:35], v[152:155], v[200:203], v[32:35]
	v_mfma_f32_16x16x32_bf16 v[20:23], v[144:147], v[208:211], v[20:23]
	v_mfma_f32_16x16x32_bf16 v[16:19], v[152:155], v[208:211], v[16:19]
	v_mfma_f32_16x16x32_bf16 v[4:7], v[144:147], v[216:219], v[4:7]
	v_mfma_f32_16x16x32_bf16 v[0:3], v[152:155], v[216:219], v[0:3]
	v_mfma_f32_16x16x32_bf16 v[52:55], v[148:151], v[196:199], v[52:55]
	v_mfma_f32_16x16x32_bf16 v[48:51], v[164:167], v[196:199], v[48:51]
	v_mfma_f32_16x16x32_bf16 v[36:39], v[148:151], v[204:207], v[36:39]
	v_mfma_f32_16x16x32_bf16 v[32:35], v[164:167], v[204:207], v[32:35]
	v_mfma_f32_16x16x32_bf16 v[20:23], v[148:151], v[212:215], v[20:23]
	v_mfma_f32_16x16x32_bf16 v[16:19], v[164:167], v[212:215], v[16:19]
	v_mfma_f32_16x16x32_bf16 v[4:7], v[148:151], v[220:223], v[4:7]
	v_mfma_f32_16x16x32_bf16 v[0:3], v[164:167], v[220:223], v[0:3]
	s_barrier
	s_movk_i32 s6, 0x100
	s_andn2_b64 vcc, exec, s[54:55]
	s_mov_b64 s[56:57], -1
	s_mov_b64 s[54:55], 0

; #define PG8_STAGE(bufoff, gbase, voff) do { _Pragma("unroll") for (int _i = 0; _i < 2; ++_i) \
;         __builtin_amdgcn_global_load_lds((const unsigned*)((const char*)(gbase) + (voff)[_i]), (LAS unsigned*)(lds + (bufoff) + ldsw + _i * 8192), 16, 0, 0); } while (0)
; #define PG8_LDA(dst, b, h) do { _Pragma("unroll") for (int m = 0; m < 4; ++m) _Pragma("unroll") for (int k = 0; k < 2; ++k) dst[m][k] = *(const LAS bf16x8*)(lds + PG8_SA(b, h) + aoff + m * 2048 + k * 1024); } while (0)
; #define PG8_LDB(dst, b, h) do { _Pragma("unroll") for (int n = 0; n < 2; ++n) _Pragma("unroll") for (int k = 0; k < 2; ++k) dst[n][k] = *(const LAS bf16x8*)(lds + PG8_SB(b, h) + boff + n * 2048 + k * 1024); } while (0)
; #define PG8_WAIT_V(n) asm volatile("s_waitcnt vmcnt(" #n ")" ::: "memory")
; #define PG8_WAIT_L(n) asm volatile("s_waitcnt lgkmcnt(" #n ")" ::: "memory")
; #define PG8_BAR __builtin_amdgcn_s_barrier()
; #define PG8_SCHED __builtin_amdgcn_sched_barrier(0)
; template <class Epi, class Sched>
; __device__ __forceinline__ void gemm_phase(LAS unsigned char* lds, const Gemm g, const Sched& S, const Epi& E) {
;     ...
;         const bool has_next = S.next(ui + 1, nxt);
;         const char* nA = has_next ? (const char*)g.A + (size_t)nxt.pm * tstepA + (size_t)nxt.pn * apn : cA; const char* nB = has_next ? (const char*)g.Bt + (size_t)nxt.pn * tstepB : cB;
;         for (int t = 0; t < nt; t += 2) {
;             const bool last = (t == nt - 2);
;             const char* a1 = cA + (size_t)(t + 1) * kstep;
;             const char* a2 = last ? nA : cA + (size_t)(t + 2) * kstep; const char* b2 = last ? nB : cB + (size_t)(t + 2) * kstep;
;             const char* a3 = a2 + kstep; const char* b3 = b2 + kstep;
;             PG8_LDB(B0, 0, 0); PG8_LDB(B1, 0, 1); PG8_SCHED; PG8_LDA(At, 0, 0); PG8_STAGE(PG8_SA(1, 1), a1 + hstepA, voffA);
;             PG8_WAIT_V(8); PG8_WAIT_L(0); PG8_BAR; PG8_MMA(0, 0, At, B0); PG8_MMA(0, 1, At, B1); PG8_BAR; PG8_SCHED;
;             PG8_LDA(At, 0, 1); PG8_STAGE(PG8_SB(0, 0), b2, voffB); PG8_STAGE(PG8_SB(0, 1), b2 + hstepB, voffB); PG8_STAGE(PG8_SA(0, 0), a2, voffA);
;     ...
;         for (int a = 0; a < 2; ++a)
; #pragma unroll
;             for (int b = 0; b < 2; ++b)
; #pragma unroll
;                 for (int m = 0; m < 4; ++m)
; #pragma unroll
;                     for (int n = 0; n < 2; ++n) acc[a][b][m][n] = (f32x4){0.f, 0.f, 0.f, 0.f};
.LBB0_717:
	s_ashr_i32 s23, s22, 31
	s_lshl_b64 s[14:15], s[22:23], 19
	s_add_u32 s34, s84, s14
	s_addc_u32 s35, s85, s15
	s_and_b64 s[14:15], s[42:43], exec
	s_cselect_b32 s23, s35, s7
	s_cselect_b32 s53, s34, s6
	s_ashr_i32 s19, s18, 31
	s_lshl_b64 s[14:15], s[18:19], 19
	s_add_u32 s40, s28, s14
	s_addc_u32 s41, s48, s15
	s_and_b64 s[14:15], s[42:43], exec
	s_cselect_b32 s19, s41, s47
	s_cselect_b32 s54, s40, s46
	s_add_u32 s44, s6, 0x40080
	s_addc_u32 s45, s7, 0
	s_add_u32 s46, s46, 0x100
	s_addc_u32 s47, s47, 0
	s_mov_b32 s55, -2
	s_add_u32 s0, s44, 0xfffc0080
	s_addc_u32 s6, s45, -1
	s_add_i32 s26, 0, 0x10000
	s_cmp_eq_u32 s55, 12
	s_cselect_b32 s15, s23, s6
	s_cselect_b32 s14, s53, s0
	v_add_u32_e32 v153, s26, v148
	s_cselect_b32 s7, s19, s47
	s_cselect_b32 s6, s54, s46
	s_add_i32 s0, 0, 0x14000
	ds_read_b128 v[142:145], v153
	ds_read_b128 v[154:157], v153 offset:1024
	ds_read_b128 v[162:165], v153 offset:2048
	ds_read_b128 v[166:169], v153 offset:3072
	v_add_u32_e32 v153, s0, v148
	ds_read_b128 v[170:173], v153
	ds_read_b128 v[174:177], v153 offset:1024
	ds_read_b128 v[190:193], v153 offset:2048
	ds_read_b128 v[196:199], v153 offset:3072
	v_lshl_add_u64 v[158:159], s[44:45], 0, v[138:139]
	s_add_i32 m0, s49, 0xc000
	ds_read_b128 v[200:203], v152
	ds_read_b128 v[204:207], v152 offset:1024
	ds_read_b128 v[208:211], v152 offset:2048
	ds_read_b128 v[212:215], v152 offset:3072
	ds_read_b128 v[216:219], v152 offset:4096
	ds_read_b128 v[220:223], v152 offset:5120
	ds_read_b128 v[224:227], v152 offset:6144
	ds_read_b128 v[228:231], v152 offset:7168
	global_load_lds_dwordx4 v[158:159], off
	v_lshl_add_u64 v[158:159], s[44:45], 0, v[140:141]
	s_add_i32 m0, s49, 0xe000
	s_nop 0
	global_load_lds_dwordx4 v[158:159], off
	s_waitcnt vmcnt(8)
	s_waitcnt lgkmcnt(0)
	s_barrier
	s_waitcnt lgkmcnt(0)
	v_mfma_f32_16x16x32_bf16 v[128:131], v[142:145], v[200:203], 0
	v_mfma_f32_16x16x32_bf16 v[124:127], v[162:165], v[200:203], 0
	v_mfma_f32_16x16x32_bf16 v[112:115], v[142:145], v[208:211], 0
	v_mfma_f32_16x16x32_bf16 v[108:111], v[162:165], v[208:211], 0
	v_mfma_f32_16x16x32_bf16 v[96:99], v[142:145], v[216:219], 0
	v_mfma_f32_16x16x32_bf16 v[92:95], v[162:165], v[216:219], 0
	v_mfma_f32_16x16x32_bf16 v[80:83], v[142:145], v[224:227], 0
	v_mfma_f32_16x16x32_bf16 v[76:79], v[162:165], v[224:227], 0
	v_mfma_f32_16x16x32_bf16 v[128:131], v[154:157], v[204:207], v[128:131]
	v_mfma_f32_16x16x32_bf16 v[124:127], v[166:169], v[204:207], v[124:127]
	v_mfma_f32_16x16x32_bf16 v[112:115], v[154:157], v[212:215], v[112:115]
	v_mfma_f32_16x16x32_bf16 v[108:111], v[166:169], v[212:215], v[108:111]
	v_mfma_f32_16x16x32_bf16 v[96:99], v[154:157], v[220:223], v[96:99]
	v_mfma_f32_16x16x32_bf16 v[92:95], v[166:169], v[220:223], v[92:95]
	v_mfma_f32_16x16x32_bf16 v[80:83], v[154:157], v[228:231], v[80:83]
	v_mfma_f32_16x16x32_bf16 v[76:79], v[166:169], v[228:231], v[76:79]
	v_mfma_f32_16x16x32_bf16 v[120:123], v[170:173], v[200:203], 0
	v_mfma_f32_16x16x32_bf16 v[116:119], v[190:193], v[200:203], 0
	v_mfma_f32_16x16x32_bf16 v[104:107], v[170:173], v[208:211], 0
	v_mfma_f32_16x16x32_bf16 v[100:103], v[190:193], v[208:211], 0
	v_mfma_f32_16x16x32_bf16 v[88:91], v[170:173], v[216:219], 0
	v_mfma_f32_16x16x32_bf16 v[84:87], v[190:193], v[216:219], 0
	v_mfma_f32_16x16x32_bf16 v[72:75], v[170:173], v[224:227], 0
	v_mfma_f32_16x16x32_bf16 v[68:71], v[190:193], v[224:227], 0
	v_mfma_f32_16x16x32_bf16 v[120:123], v[174:177], v[204:207], v[120:123]
	v_mfma_f32_16x16x32_bf16 v[116:119], v[196:199], v[204:207], v[116:119]
	v_mfma_f32_16x16x32_bf16 v[104:107], v[174:177], v[212:215], v[104:107]
	v_mfma_f32_16x16x32_bf16 v[100:103], v[196:199], v[212:215], v[100:103]
	v_mfma_f32_16x16x32_bf16 v[88:91], v[174:177], v[220:223], v[88:91]
	v_mfma_f32_16x16x32_bf16 v[84:87], v[196:199], v[220:223], v[84:87]
	v_mfma_f32_16x16x32_bf16 v[72:75], v[174:177], v[228:231], v[72:75]
	v_mfma_f32_16x16x32_bf16 v[68:71], v[196:199], v[228:231], v[68:71]
	s_barrier
	s_add_i32 s26, s26, s20
	v_lshl_add_u64 v[158:159], s[6:7], 0, v[160:161]
	s_mov_b32 m0, s26
	ds_read_b128 v[200:203], v152 offset:16384
	ds_read_b128 v[204:207], v152 offset:17408
	ds_read_b128 v[208:211], v152 offset:18432
	ds_read_b128 v[212:215], v152 offset:19456
	ds_read_b128 v[216:219], v152 offset:20480
	ds_read_b128 v[220:223], v152 offset:21504
	ds_read_b128 v[224:227], v152 offset:22528
	ds_read_b128 v[228:231], v152 offset:23552
	global_load_lds_dwordx4 v[158:159], off
	s_add_i32 m0, s26, 0x2000
	s_add_u32 s56, s6, 0x40000
	v_lshl_add_u64 v[232:233], s[6:7], 0, v[136:137]
	s_addc_u32 s57, s7, 0
	s_add_i32 s0, s0, s20
	global_load_lds_dwordx4 v[232:233], off
	v_lshl_add_u64 v[234:235], s[56:57], 0, v[160:161]
	s_mov_b32 m0, s0
	v_lshl_add_u64 v[236:237], s[14:15], 0, v[134:135]
	global_load_lds_dwordx4 v[234:235], off
	v_lshl_add_u64 v[234:235], s[56:57], 0, v[136:137]
	s_add_i32 m0, s0, 0x2000
	s_nop 0
	global_load_lds_dwordx4 v[234:235], off
	v_lshl_add_u64 v[234:235], s[14:15], 0, v[132:133]
	s_mov_b32 m0, s49
	s_nop 0
	global_load_lds_dwordx4 v[234:235], off
	s_mov_b32 m0, s50
	s_nop 0
	global_load_lds_dwordx4 v[236:237], off
	s_waitcnt vmcnt(8)
	s_waitcnt lgkmcnt(0)
	s_barrier
; #define PG8_STAGE(bufoff, gbase, voff) do { _Pragma("unroll") for (int _i = 0; _i < 2; ++_i) \
;         __builtin_amdgcn_global_load_lds((const unsigned*)((const char*)(gbase) + (voff)[_i]), (LAS unsigned*)(lds + (bufoff) + ldsw + _i * 8192), 16, 0, 0); } while (0)
; #define PG8_LDA(dst, b, h) do { _Pragma("unroll") for (int m = 0; m < 4; ++m) _Pragma("unroll") for (int k = 0; k < 2; ++k) dst[m][k] = *(const LAS bf16x8*)(lds + PG8_SA(b, h) + aoff + m * 2048 + k * 1024); } while (0)
; #define PG8_LDB(dst, b, h) do { _Pragma("unroll") for (int n = 0; n < 2; ++n) _Pragma("unroll") for (int k = 0; k < 2; ++k) dst[n][k] = *(const LAS bf16x8*)(lds + PG8_SB(b, h) + boff + n * 2048 + k * 1024); } while (0)
; #define PG8_MMA(ai, bj, At, Bt) do { __builtin_amdgcn_s_setprio(1); _Pragma("unroll") for (int m = 0; m < 4; ++m) _Pragma("unroll") for (int n = 0; n < 2; ++n) _Pragma("unroll") for (int k = 0; k < 2; ++k) \
;         acc[ai][bj][m][n] = __builtin_amdgcn_mfma_f32_16x16x32_bf16(Bt[n][k], At[m][k], acc[ai][bj][m][n], 0, 0, 0); __builtin_amdgcn_s_setprio(0); } while (0)
; #define PG8_WAIT_V(n) asm volatile("s_waitcnt vmcnt(" #n ")" ::: "memory")
; #define PG8_WAIT_L(n) asm volatile("s_waitcnt lgkmcnt(" #n ")" ::: "memory")
; #define PG8_BAR __builtin_amdgcn_s_barrier()
; #define PG8_SCHED __builtin_amdgcn_sched_barrier(0)
; template <class Epi, class Sched>
; __device__ __forceinline__ void gemm_phase(LAS unsigned char* lds, const Gemm g, const Sched& S, const Epi& E) {
;     ...
;             PG8_WAIT_V(8); PG8_WAIT_L(0); PG8_BAR; PG8_MMA(0, 0, At, B0); PG8_MMA(0, 1, At, B1); PG8_BAR; PG8_SCHED;
;             PG8_LDA(At, 0, 1); PG8_STAGE(PG8_SB(0, 0), b2, voffB); PG8_STAGE(PG8_SB(0, 1), b2 + hstepB, voffB); PG8_STAGE(PG8_SA(0, 0), a2, voffA);
;             PG8_WAIT_V(8); PG8_WAIT_L(0); PG8_BAR; PG8_MMA(1, 0, At, B0); PG8_MMA(1, 1, At, B1); PG8_BAR; PG8_SCHED;
;             PG8_LDB(B0, 1, 0); PG8_LDB(B1, 1, 1); PG8_SCHED; PG8_LDA(At, 1, 0); PG8_STAGE(PG8_SA(0, 1), a2 + hstepA, voffA);
;             PG8_WAIT_V(8); PG8_WAIT_L(0); PG8_BAR; PG8_MMA(0, 0, At, B0); PG8_MMA(0, 1, At, B1); PG8_BAR; PG8_SCHED;
;             PG8_LDA(At, 1, 1); PG8_STAGE(PG8_SB(1, 0), b3, voffB); PG8_STAGE(PG8_SB(1, 1), b3 + hstepB, voffB); PG8_STAGE(PG8_SA(1, 0), a3, voffA);
;             PG8_WAIT_V(8); PG8_WAIT_L(0); PG8_BAR; PG8_MMA(1, 0, At, B0); PG8_MMA(1, 1, At, B1); PG8_BAR; PG8_SCHED;
	s_waitcnt lgkmcnt(0)
	v_mfma_f32_16x16x32_bf16 v[64:67], v[142:145], v[200:203], 0
	v_mfma_f32_16x16x32_bf16 v[60:63], v[162:165], v[200:203], 0
	v_mfma_f32_16x16x32_bf16 v[48:51], v[142:145], v[208:211], 0
	v_mfma_f32_16x16x32_bf16 v[44:47], v[162:165], v[208:211], 0
	v_mfma_f32_16x16x32_bf16 v[32:35], v[142:145], v[216:219], 0
	v_mfma_f32_16x16x32_bf16 v[28:31], v[162:165], v[216:219], 0
	v_mfma_f32_16x16x32_bf16 v[16:19], v[142:145], v[224:227], 0
	v_mfma_f32_16x16x32_bf16 v[12:15], v[162:165], v[224:227], 0
	v_mfma_f32_16x16x32_bf16 v[64:67], v[154:157], v[204:207], v[64:67]
	v_mfma_f32_16x16x32_bf16 v[60:63], v[166:169], v[204:207], v[60:63]
	v_mfma_f32_16x16x32_bf16 v[48:51], v[154:157], v[212:215], v[48:51]
	v_mfma_f32_16x16x32_bf16 v[44:47], v[166:169], v[212:215], v[44:47]
	v_mfma_f32_16x16x32_bf16 v[32:35], v[154:157], v[220:223], v[32:35]
	v_mfma_f32_16x16x32_bf16 v[28:31], v[166:169], v[220:223], v[28:31]
	v_mfma_f32_16x16x32_bf16 v[16:19], v[154:157], v[228:231], v[16:19]
	v_mfma_f32_16x16x32_bf16 v[12:15], v[166:169], v[228:231], v[12:15]
	v_mfma_f32_16x16x32_bf16 v[56:59], v[170:173], v[200:203], 0
	v_mfma_f32_16x16x32_bf16 v[52:55], v[190:193], v[200:203], 0
	v_mfma_f32_16x16x32_bf16 v[40:43], v[170:173], v[208:211], 0
	v_mfma_f32_16x16x32_bf16 v[36:39], v[190:193], v[208:211], 0
	v_mfma_f32_16x16x32_bf16 v[24:27], v[170:173], v[216:219], 0
	v_mfma_f32_16x16x32_bf16 v[20:23], v[190:193], v[216:219], 0
	v_mfma_f32_16x16x32_bf16 v[8:11], v[170:173], v[224:227], 0
	v_mfma_f32_16x16x32_bf16 v[4:7], v[190:193], v[224:227], 0
	v_mfma_f32_16x16x32_bf16 v[56:59], v[174:177], v[204:207], v[56:59]
	v_mfma_f32_16x16x32_bf16 v[52:55], v[196:199], v[204:207], v[52:55]
	v_mfma_f32_16x16x32_bf16 v[40:43], v[174:177], v[212:215], v[40:43]
	v_mfma_f32_16x16x32_bf16 v[36:39], v[196:199], v[212:215], v[36:39]
	v_mfma_f32_16x16x32_bf16 v[24:27], v[174:177], v[220:223], v[24:27]
	v_mfma_f32_16x16x32_bf16 v[20:23], v[196:199], v[220:223], v[20:23]
	v_mfma_f32_16x16x32_bf16 v[8:11], v[174:177], v[228:231], v[8:11]
	v_mfma_f32_16x16x32_bf16 v[4:7], v[196:199], v[228:231], v[4:7]
	s_barrier
	s_add_i32 s0, 0, 0x18000
	v_add_u32_e32 v153, s0, v148
	s_add_i32 s26, 0, 0x1c000
	ds_read_b128 v[142:145], v153
	ds_read_b128 v[154:157], v153 offset:1024
	ds_read_b128 v[162:165], v153 offset:2048
	ds_read_b128 v[166:169], v153 offset:3072
	v_add_u32_e32 v153, s26, v148
	ds_read_b128 v[170:173], v153
	ds_read_b128 v[174:177], v153 offset:1024
	ds_read_b128 v[190:193], v153 offset:2048
	ds_read_b128 v[196:199], v153 offset:3072
	s_add_u32 s14, s14, 0x40000
	s_addc_u32 s15, s15, 0
	s_mov_b32 m0, s51
	v_lshl_add_u64 v[238:239], s[14:15], 0, v[132:133]
	ds_read_b128 v[200:203], v152 offset:32768
	ds_read_b128 v[204:207], v152 offset:33792
	ds_read_b128 v[208:211], v152 offset:34816
	ds_read_b128 v[212:215], v152 offset:35840
	ds_read_b128 v[216:219], v152 offset:36864
	ds_read_b128 v[220:223], v152 offset:37888
	ds_read_b128 v[224:227], v152 offset:38912
	ds_read_b128 v[228:231], v152 offset:39936
	global_load_lds_dwordx4 v[238:239], off
	v_lshl_add_u64 v[238:239], s[14:15], 0, v[134:135]
	s_mov_b32 m0, s52
	s_nop 0
	global_load_lds_dwordx4 v[238:239], off
	s_waitcnt vmcnt(8)
	s_waitcnt lgkmcnt(0)
	s_barrier
	s_waitcnt lgkmcnt(0)
	v_mfma_f32_16x16x32_bf16 v[128:131], v[142:145], v[200:203], v[128:131]
	v_mfma_f32_16x16x32_bf16 v[124:127], v[162:165], v[200:203], v[124:127]
	v_mfma_f32_16x16x32_bf16 v[112:115], v[142:145], v[208:211], v[112:115]
	v_mfma_f32_16x16x32_bf16 v[108:111], v[162:165], v[208:211], v[108:111]
	v_mfma_f32_16x16x32_bf16 v[96:99], v[142:145], v[216:219], v[96:99]
	v_mfma_f32_16x16x32_bf16 v[92:95], v[162:165], v[216:219], v[92:95]
	v_mfma_f32_16x16x32_bf16 v[80:83], v[142:145], v[224:227], v[80:83]
	v_mfma_f32_16x16x32_bf16 v[76:79], v[162:165], v[224:227], v[76:79]
	v_mfma_f32_16x16x32_bf16 v[128:131], v[154:157], v[204:207], v[128:131]
	v_mfma_f32_16x16x32_bf16 v[124:127], v[166:169], v[204:207], v[124:127]
	v_mfma_f32_16x16x32_bf16 v[112:115], v[154:157], v[212:215], v[112:115]
	v_mfma_f32_16x16x32_bf16 v[108:111], v[166:169], v[212:215], v[108:111]
	v_mfma_f32_16x16x32_bf16 v[96:99], v[154:157], v[220:223], v[96:99]
	v_mfma_f32_16x16x32_bf16 v[92:95], v[166:169], v[220:223], v[92:95]
	v_mfma_f32_16x16x32_bf16 v[80:83], v[154:157], v[228:231], v[80:83]
	v_mfma_f32_16x16x32_bf16 v[76:79], v[166:169], v[228:231], v[76:79]
	v_mfma_f32_16x16x32_bf16 v[120:123], v[170:173], v[200:203], v[120:123]
	v_mfma_f32_16x16x32_bf16 v[116:119], v[190:193], v[200:203], v[116:119]
	v_mfma_f32_16x16x32_bf16 v[104:107], v[170:173], v[208:211], v[104:107]
	v_mfma_f32_16x16x32_bf16 v[100:103], v[190:193], v[208:211], v[100:103]
	v_mfma_f32_16x16x32_bf16 v[88:91], v[170:173], v[216:219], v[88:91]
	v_mfma_f32_16x16x32_bf16 v[84:87], v[190:193], v[216:219], v[84:87]
	v_mfma_f32_16x16x32_bf16 v[72:75], v[170:173], v[224:227], v[72:75]
	v_mfma_f32_16x16x32_bf16 v[68:71], v[190:193], v[224:227], v[68:71]
	v_mfma_f32_16x16x32_bf16 v[120:123], v[174:177], v[204:207], v[120:123]
	v_mfma_f32_16x16x32_bf16 v[116:119], v[196:199], v[204:207], v[116:119]
	v_mfma_f32_16x16x32_bf16 v[104:107], v[174:177], v[212:215], v[104:107]
	v_mfma_f32_16x16x32_bf16 v[100:103], v[196:199], v[212:215], v[100:103]
	v_mfma_f32_16x16x32_bf16 v[88:91], v[174:177], v[220:223], v[88:91]
	v_mfma_f32_16x16x32_bf16 v[84:87], v[196:199], v[220:223], v[84:87]
	v_mfma_f32_16x16x32_bf16 v[72:75], v[174:177], v[228:231], v[72:75]
	v_mfma_f32_16x16x32_bf16 v[68:71], v[196:199], v[228:231], v[68:71]
	s_barrier
; #define PG8_STAGE(bufoff, gbase, voff) do { _Pragma("unroll") for (int _i = 0; _i < 2; ++_i) \
;         __builtin_amdgcn_global_load_lds((const unsigned*)((const char*)(gbase) + (voff)[_i]), (LAS unsigned*)(lds + (bufoff) + ldsw + _i * 8192), 16, 0, 0); } while (0)
; #define PG8_LDA(dst, b, h) do { _Pragma("unroll") for (int m = 0; m < 4; ++m) _Pragma("unroll") for (int k = 0; k < 2; ++k) dst[m][k] = *(const LAS bf16x8*)(lds + PG8_SA(b, h) + aoff + m * 2048 + k * 1024); } while (0)
; #define PG8_MMA(ai, bj, At, Bt) do { __builtin_amdgcn_s_setprio(1); _Pragma("unroll") for (int m = 0; m < 4; ++m) _Pragma("unroll") for (int n = 0; n < 2; ++n) _Pragma("unroll") for (int k = 0; k < 2; ++k) \
;         acc[ai][bj][m][n] = __builtin_amdgcn_mfma_f32_16x16x32_bf16(Bt[n][k], At[m][k], acc[ai][bj][m][n], 0, 0, 0); __builtin_amdgcn_s_setprio(0); } while (0)
; #define PG8_WAIT_V(n) asm volatile("s_waitcnt vmcnt(" #n ")" ::: "memory")
; #define PG8_WAIT_L(n) asm volatile("s_waitcnt lgkmcnt(" #n ")" ::: "memory")
; #define PG8_BAR __builtin_amdgcn_s_barrier()
; #define PG8_SCHED __builtin_amdgcn_sched_barrier(0)
; template <class Epi, class Sched>
; __device__ __forceinline__ void gemm_phase(LAS unsigned char* lds, const Gemm g, const Sched& S, const Epi& E) {
;     ...
;             PG8_LDA(At, 1, 1); PG8_STAGE(PG8_SB(1, 0), b3, voffB); PG8_STAGE(PG8_SB(1, 1), b3 + hstepB, voffB); PG8_STAGE(PG8_SA(1, 0), a3, voffA);
;             PG8_WAIT_V(8); PG8_WAIT_L(0); PG8_BAR; PG8_MMA(1, 0, At, B0); PG8_MMA(1, 1, At, B1); PG8_BAR; PG8_SCHED;
;         }
	s_add_i32 s0, s0, s20
	v_lshl_add_u64 v[158:159], v[158:159], 0, s[30:31]
	s_mov_b32 m0, s0
	ds_read_b128 v[200:203], v152 offset:49152
	ds_read_b128 v[204:207], v152 offset:50176
	ds_read_b128 v[208:211], v152 offset:51200
	ds_read_b128 v[212:215], v152 offset:52224
	ds_read_b128 v[216:219], v152 offset:53248
	ds_read_b128 v[220:223], v152 offset:54272
	ds_read_b128 v[224:227], v152 offset:55296
	ds_read_b128 v[228:231], v152 offset:56320
	global_load_lds_dwordx4 v[158:159], off
	s_add_i32 m0, s0, 0x2000
	s_add_u32 s6, s6, 0x40080
	v_lshl_add_u64 v[158:159], v[232:233], 0, s[30:31]
	s_addc_u32 s7, s7, 0
	s_add_i32 s0, s26, s20
	global_load_lds_dwordx4 v[158:159], off
	v_lshl_add_u64 v[158:159], s[6:7], 0, v[160:161]
	s_mov_b32 m0, s0
	s_nop 0
	global_load_lds_dwordx4 v[158:159], off
	v_lshl_add_u64 v[158:159], s[6:7], 0, v[136:137]
	s_add_i32 m0, s0, 0x2000
	s_nop 0
	global_load_lds_dwordx4 v[158:159], off
	v_lshl_add_u64 v[158:159], v[234:235], 0, s[30:31]
	s_mov_b32 m0, s24
	s_nop 0
	global_load_lds_dwordx4 v[158:159], off
	v_lshl_add_u64 v[158:159], v[236:237], 0, s[30:31]
	s_mov_b32 m0, s25
	s_nop 0
	global_load_lds_dwordx4 v[158:159], off
	s_waitcnt vmcnt(8)
	s_waitcnt lgkmcnt(0)
	s_barrier
	s_waitcnt lgkmcnt(0)
	v_mfma_f32_16x16x32_bf16 v[64:67], v[142:145], v[200:203], v[64:67]
	v_mfma_f32_16x16x32_bf16 v[60:63], v[162:165], v[200:203], v[60:63]
	v_mfma_f32_16x16x32_bf16 v[48:51], v[142:145], v[208:211], v[48:51]
	v_mfma_f32_16x16x32_bf16 v[44:47], v[162:165], v[208:211], v[44:47]
	v_mfma_f32_16x16x32_bf16 v[32:35], v[142:145], v[216:219], v[32:35]
	v_mfma_f32_16x16x32_bf16 v[28:31], v[162:165], v[216:219], v[28:31]
	v_mfma_f32_16x16x32_bf16 v[16:19], v[142:145], v[224:227], v[16:19]
	v_mfma_f32_16x16x32_bf16 v[12:15], v[162:165], v[224:227], v[12:15]
	v_mfma_f32_16x16x32_bf16 v[64:67], v[154:157], v[204:207], v[64:67]
	v_mfma_f32_16x16x32_bf16 v[60:63], v[166:169], v[204:207], v[60:63]
	v_mfma_f32_16x16x32_bf16 v[48:51], v[154:157], v[212:215], v[48:51]
	v_mfma_f32_16x16x32_bf16 v[44:47], v[166:169], v[212:215], v[44:47]
	v_mfma_f32_16x16x32_bf16 v[32:35], v[154:157], v[220:223], v[32:35]
	v_mfma_f32_16x16x32_bf16 v[28:31], v[166:169], v[220:223], v[28:31]
	v_mfma_f32_16x16x32_bf16 v[16:19], v[154:157], v[228:231], v[16:19]
	v_mfma_f32_16x16x32_bf16 v[12:15], v[166:169], v[228:231], v[12:15]
	v_mfma_f32_16x16x32_bf16 v[56:59], v[170:173], v[200:203], v[56:59]
	v_mfma_f32_16x16x32_bf16 v[52:55], v[190:193], v[200:203], v[52:55]
	v_mfma_f32_16x16x32_bf16 v[40:43], v[170:173], v[208:211], v[40:43]
	v_mfma_f32_16x16x32_bf16 v[36:39], v[190:193], v[208:211], v[36:39]
	v_mfma_f32_16x16x32_bf16 v[24:27], v[170:173], v[216:219], v[24:27]
	v_mfma_f32_16x16x32_bf16 v[20:23], v[190:193], v[216:219], v[20:23]
	v_mfma_f32_16x16x32_bf16 v[8:11], v[170:173], v[224:227], v[8:11]
	v_mfma_f32_16x16x32_bf16 v[4:7], v[190:193], v[224:227], v[4:7]
	v_mfma_f32_16x16x32_bf16 v[56:59], v[174:177], v[204:207], v[56:59]
	v_mfma_f32_16x16x32_bf16 v[52:55], v[196:199], v[204:207], v[52:55]
	v_mfma_f32_16x16x32_bf16 v[40:43], v[174:177], v[212:215], v[40:43]
	v_mfma_f32_16x16x32_bf16 v[36:39], v[196:199], v[212:215], v[36:39]
	v_mfma_f32_16x16x32_bf16 v[24:27], v[174:177], v[220:223], v[24:27]
	v_mfma_f32_16x16x32_bf16 v[20:23], v[196:199], v[220:223], v[20:23]
	v_mfma_f32_16x16x32_bf16 v[8:11], v[174:177], v[228:231], v[8:11]
	v_mfma_f32_16x16x32_bf16 v[4:7], v[196:199], v[228:231], v[4:7]
	s_barrier
	s_add_i32 s55, s55, 2
	s_add_u32 s44, s44, 0x100
	s_addc_u32 s45, s45, 0
	s_add_u32 s46, s46, 0x100
	s_addc_u32 s47, s47, 0
	s_cmp_gt_u32 s55, 13

; #define PG8_STAGE(bufoff, gbase, voff) do { _Pragma("unroll") for (int _i = 0; _i < 2; ++_i) \
;         __builtin_amdgcn_global_load_lds((const unsigned*)((const char*)(gbase) + (voff)[_i]), (LAS unsigned*)(lds + (bufoff) + ldsw + _i * 8192), 16, 0, 0); } while (0)
; #define PG8_LDA(dst, b, h) do { _Pragma("unroll") for (int m = 0; m < 4; ++m) _Pragma("unroll") for (int k = 0; k < 2; ++k) dst[m][k] = *(const LAS bf16x8*)(lds + PG8_SA(b, h) + aoff + m * 2048 + k * 1024); } while (0)
; #define PG8_LDB(dst, b, h) do { _Pragma("unroll") for (int n = 0; n < 2; ++n) _Pragma("unroll") for (int k = 0; k < 2; ++k) dst[n][k] = *(const LAS bf16x8*)(lds + PG8_SB(b, h) + boff + n * 2048 + k * 1024); } while (0)
; #define PG8_MMA(ai, bj, At, Bt) do { __builtin_amdgcn_s_setprio(1); _Pragma("unroll") for (int m = 0; m < 4; ++m) _Pragma("unroll") for (int n = 0; n < 2; ++n) _Pragma("unroll") for (int k = 0; k < 2; ++k) \
;         acc[ai][bj][m][n] = __builtin_amdgcn_mfma_f32_16x16x32_bf16(Bt[n][k], At[m][k], acc[ai][bj][m][n], 0, 0, 0); __builtin_amdgcn_s_setprio(0); } while (0)
; #define PG8_BAR __builtin_amdgcn_s_barrier()
; template <class Epi, class Sched>
; __device__ __forceinline__ void gemm_phase(LAS unsigned char* lds, const Gemm g, const Sched& S, const Epi& E) {
;     ...
;         const bool has_next = S.next(ui + 1, nxt);
;         const char* nA = has_next ? (const char*)g.A + (size_t)nxt.pm * tstepA + (size_t)nxt.pn * apn : cA; const char* nB = has_next ? (const char*)g.Bt + (size_t)nxt.pn * tstepB : cB;
;         for (int t = 0; t < nt; t += 2) {
;             const bool last = (t == nt - 2);
;             const char* a1 = cA + (size_t)(t + 1) * kstep;
;             const char* a2 = last ? nA : cA + (size_t)(t + 2) * kstep; const char* b2 = last ? nB : cB + (size_t)(t + 2) * kstep;
;             const char* a3 = a2 + kstep; const char* b3 = b2 + kstep;
;             PG8_LDB(B0, 0, 0); PG8_LDB(B1, 0, 1); PG8_SCHED; PG8_LDA(At, 0, 0); PG8_STAGE(PG8_SA(1, 1), a1 + hstepA, voffA);
;             PG8_WAIT_V(8); PG8_WAIT_L(0); PG8_BAR; PG8_MMA(0, 0, At, B0); PG8_MMA(0, 1, At, B1); PG8_BAR; PG8_SCHED;
;     ...
;         for (int a = 0; a < 2; ++a)
; #pragma unroll
;             for (int b = 0; b < 2; ++b)
; #pragma unroll
;                 for (int m = 0; m < 4; ++m)
; #pragma unroll
;                     for (int n = 0; n < 2; ++n) acc[a][b][m][n] = (f32x4){0.f, 0.f, 0.f, 0.f};
.LBB0_806:
	s_add_u32 s33, s46, 0x100
	s_addc_u32 s53, s47, 0
	s_mov_b32 s54, -2
	s_waitcnt lgkmcnt(0)
	s_add_u32 s46, s44, 0x100
	s_addc_u32 s47, s45, 0
	s_add_i32 s0, 0, 0x10000
	s_cmp_eq_u32 s54, 40
	s_cselect_b32 s15, s23, s47
	s_cselect_b32 s14, s22, s46
	s_cselect_b32 s7, s35, s53
	s_cselect_b32 s6, s34, s33
	s_add_i32 s26, 0, 0x14000
	v_add_u32_e32 v140, s0, v186
	v_add_u32_e32 v168, s26, v186
	ds_read_b128 v[128:131], v140
	ds_read_b128 v[132:135], v140 offset:1024
	ds_read_b128 v[136:139], v140 offset:2048
	ds_read_b128 v[140:143], v140 offset:3072
	ds_read_b128 v[144:147], v168
	ds_read_b128 v[148:151], v168 offset:1024
	ds_read_b128 v[152:155], v168 offset:2048
	ds_read_b128 v[168:171], v168 offset:3072
	v_lshl_add_u64 v[226:227], s[44:45], 0, v[164:165]
	s_add_i32 m0, s49, 0xc000
	ds_read_b128 v[172:175], v196
	ds_read_b128 v[198:201], v196 offset:1024
	ds_read_b128 v[202:205], v196 offset:2048
	ds_read_b128 v[206:209], v196 offset:3072
	ds_read_b128 v[210:213], v196 offset:4096
	ds_read_b128 v[214:217], v196 offset:5120
	ds_read_b128 v[218:221], v196 offset:6144
	ds_read_b128 v[222:225], v196 offset:7168
	global_load_lds_dwordx4 v[226:227], off
	v_lshl_add_u64 v[226:227], s[44:45], 0, v[166:167]
	s_add_i32 m0, s49, 0xe000
	s_nop 0
	global_load_lds_dwordx4 v[226:227], off
	s_waitcnt vmcnt(8)
	s_waitcnt lgkmcnt(0)
	s_barrier
	s_waitcnt lgkmcnt(0)
	v_mfma_f32_16x16x32_bf16 v[124:127], v[128:131], v[172:175], 0
	v_mfma_f32_16x16x32_bf16 v[120:123], v[136:139], v[172:175], 0
	v_mfma_f32_16x16x32_bf16 v[108:111], v[128:131], v[202:205], 0
	v_mfma_f32_16x16x32_bf16 v[104:107], v[136:139], v[202:205], 0
	v_mfma_f32_16x16x32_bf16 v[92:95], v[128:131], v[210:213], 0
	v_mfma_f32_16x16x32_bf16 v[88:91], v[136:139], v[210:213], 0
	v_mfma_f32_16x16x32_bf16 v[76:79], v[128:131], v[218:221], 0
	v_mfma_f32_16x16x32_bf16 v[72:75], v[136:139], v[218:221], 0
	v_mfma_f32_16x16x32_bf16 v[124:127], v[132:135], v[198:201], v[124:127]
	v_mfma_f32_16x16x32_bf16 v[120:123], v[140:143], v[198:201], v[120:123]
	v_mfma_f32_16x16x32_bf16 v[108:111], v[132:135], v[206:209], v[108:111]
	v_mfma_f32_16x16x32_bf16 v[104:107], v[140:143], v[206:209], v[104:107]
	v_mfma_f32_16x16x32_bf16 v[92:95], v[132:135], v[214:217], v[92:95]
	v_mfma_f32_16x16x32_bf16 v[88:91], v[140:143], v[214:217], v[88:91]
	v_mfma_f32_16x16x32_bf16 v[76:79], v[132:135], v[222:225], v[76:79]
	v_mfma_f32_16x16x32_bf16 v[72:75], v[140:143], v[222:225], v[72:75]
	v_mfma_f32_16x16x32_bf16 v[116:119], v[144:147], v[172:175], 0
	v_mfma_f32_16x16x32_bf16 v[112:115], v[152:155], v[172:175], 0
	v_mfma_f32_16x16x32_bf16 v[100:103], v[144:147], v[202:205], 0
	v_mfma_f32_16x16x32_bf16 v[96:99], v[152:155], v[202:205], 0
	v_mfma_f32_16x16x32_bf16 v[84:87], v[144:147], v[210:213], 0
	v_mfma_f32_16x16x32_bf16 v[80:83], v[152:155], v[210:213], 0
	v_mfma_f32_16x16x32_bf16 v[68:71], v[144:147], v[218:221], 0
	v_mfma_f32_16x16x32_bf16 v[64:67], v[152:155], v[218:221], 0
	v_mfma_f32_16x16x32_bf16 v[116:119], v[148:151], v[198:201], v[116:119]
	v_mfma_f32_16x16x32_bf16 v[112:115], v[168:171], v[198:201], v[112:115]
	v_mfma_f32_16x16x32_bf16 v[100:103], v[148:151], v[206:209], v[100:103]
	v_mfma_f32_16x16x32_bf16 v[96:99], v[168:171], v[206:209], v[96:99]
	v_mfma_f32_16x16x32_bf16 v[84:87], v[148:151], v[214:217], v[84:87]
	v_mfma_f32_16x16x32_bf16 v[80:83], v[168:171], v[214:217], v[80:83]
	v_mfma_f32_16x16x32_bf16 v[68:71], v[148:151], v[222:225], v[68:71]
	v_mfma_f32_16x16x32_bf16 v[64:67], v[168:171], v[222:225], v[64:67]
	s_barrier
	s_add_i32 s0, s0, s20
	v_lshl_add_u64 v[226:227], s[6:7], 0, v[160:161]
	s_mov_b32 m0, s0
	ds_read_b128 v[172:175], v196 offset:16384
	ds_read_b128 v[198:201], v196 offset:17408
	ds_read_b128 v[202:205], v196 offset:18432
	ds_read_b128 v[206:209], v196 offset:19456
	ds_read_b128 v[210:213], v196 offset:20480
	ds_read_b128 v[214:217], v196 offset:21504
	ds_read_b128 v[218:221], v196 offset:22528
	ds_read_b128 v[222:225], v196 offset:23552
	global_load_lds_dwordx4 v[226:227], off
	s_add_i32 m0, s0, 0x2000
	s_add_u32 s44, s6, 0xb0000
	v_lshl_add_u64 v[228:229], s[6:7], 0, v[162:163]
	s_addc_u32 s45, s7, 0
	s_add_i32 s0, s26, s20
	global_load_lds_dwordx4 v[228:229], off
	v_lshl_add_u64 v[230:231], s[44:45], 0, v[160:161]
	s_mov_b32 m0, s0
	v_lshl_add_u64 v[232:233], s[14:15], 0, v[158:159]
	global_load_lds_dwordx4 v[230:231], off
	v_lshl_add_u64 v[230:231], s[44:45], 0, v[162:163]
	s_add_i32 m0, s0, 0x2000
	s_nop 0
	global_load_lds_dwordx4 v[230:231], off
	v_lshl_add_u64 v[230:231], s[14:15], 0, v[156:157]
	s_mov_b32 m0, s49
	s_nop 0
	global_load_lds_dwordx4 v[230:231], off
	s_mov_b32 m0, s50
	s_nop 0
	global_load_lds_dwordx4 v[232:233], off
	s_waitcnt vmcnt(8)
	s_waitcnt lgkmcnt(0)
	s_barrier
; #define PG8_STAGE(bufoff, gbase, voff) do { _Pragma("unroll") for (int _i = 0; _i < 2; ++_i) \
;         __builtin_amdgcn_global_load_lds((const unsigned*)((const char*)(gbase) + (voff)[_i]), (LAS unsigned*)(lds + (bufoff) + ldsw + _i * 8192), 16, 0, 0); } while (0)
; #define PG8_LDA(dst, b, h) do { _Pragma("unroll") for (int m = 0; m < 4; ++m) _Pragma("unroll") for (int k = 0; k < 2; ++k) dst[m][k] = *(const LAS bf16x8*)(lds + PG8_SA(b, h) + aoff + m * 2048 + k * 1024); } while (0)
; #define PG8_LDB(dst, b, h) do { _Pragma("unroll") for (int n = 0; n < 2; ++n) _Pragma("unroll") for (int k = 0; k < 2; ++k) dst[n][k] = *(const LAS bf16x8*)(lds + PG8_SB(b, h) + boff + n * 2048 + k * 1024); } while (0)
; #define PG8_MMA(ai, bj, At, Bt) do { __builtin_amdgcn_s_setprio(1); _Pragma("unroll") for (int m = 0; m < 4; ++m) _Pragma("unroll") for (int n = 0; n < 2; ++n) _Pragma("unroll") for (int k = 0; k < 2; ++k) \
;         acc[ai][bj][m][n] = __builtin_amdgcn_mfma_f32_16x16x32_bf16(Bt[n][k], At[m][k], acc[ai][bj][m][n], 0, 0, 0); __builtin_amdgcn_s_setprio(0); } while (0)
; #define PG8_WAIT_V(n) asm volatile("s_waitcnt vmcnt(" #n ")" ::: "memory")
; #define PG8_WAIT_L(n) asm volatile("s_waitcnt lgkmcnt(" #n ")" ::: "memory")
; #define PG8_BAR __builtin_amdgcn_s_barrier()
; #define PG8_SCHED __builtin_amdgcn_sched_barrier(0)
; template <class Epi, class Sched>
; __device__ __forceinline__ void gemm_phase(LAS unsigned char* lds, const Gemm g, const Sched& S, const Epi& E) {
;     ...
;             PG8_WAIT_V(8); PG8_WAIT_L(0); PG8_BAR; PG8_MMA(1, 0, At, B0); PG8_MMA(1, 1, At, B1); PG8_BAR; PG8_SCHED;
;             PG8_LDB(B0, 1, 0); PG8_LDB(B1, 1, 1); PG8_SCHED; PG8_LDA(At, 1, 0); PG8_STAGE(PG8_SA(0, 1), a2 + hstepA, voffA);
;             PG8_WAIT_V(8); PG8_WAIT_L(0); PG8_BAR; PG8_MMA(0, 0, At, B0); PG8_MMA(0, 1, At, B1); PG8_BAR; PG8_SCHED;
	s_waitcnt lgkmcnt(0)
	v_mfma_f32_16x16x32_bf16 v[60:63], v[128:131], v[172:175], 0
	v_mfma_f32_16x16x32_bf16 v[56:59], v[136:139], v[172:175], 0
	v_mfma_f32_16x16x32_bf16 v[44:47], v[128:131], v[202:205], 0
	v_mfma_f32_16x16x32_bf16 v[40:43], v[136:139], v[202:205], 0
	v_mfma_f32_16x16x32_bf16 v[28:31], v[128:131], v[210:213], 0
	v_mfma_f32_16x16x32_bf16 v[24:27], v[136:139], v[210:213], 0
	v_mfma_f32_16x16x32_bf16 v[12:15], v[128:131], v[218:221], 0
	v_mfma_f32_16x16x32_bf16 v[8:11], v[136:139], v[218:221], 0
	v_mfma_f32_16x16x32_bf16 v[60:63], v[132:135], v[198:201], v[60:63]
	v_mfma_f32_16x16x32_bf16 v[56:59], v[140:143], v[198:201], v[56:59]
	v_mfma_f32_16x16x32_bf16 v[44:47], v[132:135], v[206:209], v[44:47]
	v_mfma_f32_16x16x32_bf16 v[40:43], v[140:143], v[206:209], v[40:43]
	v_mfma_f32_16x16x32_bf16 v[28:31], v[132:135], v[214:217], v[28:31]
	v_mfma_f32_16x16x32_bf16 v[24:27], v[140:143], v[214:217], v[24:27]
	v_mfma_f32_16x16x32_bf16 v[12:15], v[132:135], v[222:225], v[12:15]
	v_mfma_f32_16x16x32_bf16 v[8:11], v[140:143], v[222:225], v[8:11]
	v_mfma_f32_16x16x32_bf16 v[52:55], v[144:147], v[172:175], 0
	v_mfma_f32_16x16x32_bf16 v[48:51], v[152:155], v[172:175], 0
	v_mfma_f32_16x16x32_bf16 v[36:39], v[144:147], v[202:205], 0
	v_mfma_f32_16x16x32_bf16 v[32:35], v[152:155], v[202:205], 0
	v_mfma_f32_16x16x32_bf16 v[20:23], v[144:147], v[210:213], 0
	v_mfma_f32_16x16x32_bf16 v[16:19], v[152:155], v[210:213], 0
	v_mfma_f32_16x16x32_bf16 v[4:7], v[144:147], v[218:221], 0
	v_mfma_f32_16x16x32_bf16 v[0:3], v[152:155], v[218:221], 0
	v_mfma_f32_16x16x32_bf16 v[52:55], v[148:151], v[198:201], v[52:55]
	v_mfma_f32_16x16x32_bf16 v[48:51], v[168:171], v[198:201], v[48:51]
	v_mfma_f32_16x16x32_bf16 v[36:39], v[148:151], v[206:209], v[36:39]
	v_mfma_f32_16x16x32_bf16 v[32:35], v[168:171], v[206:209], v[32:35]
	v_mfma_f32_16x16x32_bf16 v[20:23], v[148:151], v[214:217], v[20:23]
	v_mfma_f32_16x16x32_bf16 v[16:19], v[168:171], v[214:217], v[16:19]
	v_mfma_f32_16x16x32_bf16 v[4:7], v[148:151], v[222:225], v[4:7]
	v_mfma_f32_16x16x32_bf16 v[0:3], v[168:171], v[222:225], v[0:3]
	s_barrier
	s_add_i32 s0, 0, 0x18000
	s_add_i32 s26, 0, 0x1c000
	v_add_u32_e32 v140, s0, v186
	v_add_u32_e32 v168, s26, v186
	ds_read_b128 v[128:131], v140
	ds_read_b128 v[132:135], v140 offset:1024
	ds_read_b128 v[136:139], v140 offset:2048
	ds_read_b128 v[140:143], v140 offset:3072
	ds_read_b128 v[144:147], v168
	ds_read_b128 v[148:151], v168 offset:1024
	ds_read_b128 v[152:155], v168 offset:2048
	ds_read_b128 v[168:171], v168 offset:3072
	s_add_u32 s14, s14, 0xb0000
	s_addc_u32 s15, s15, 0
	s_mov_b32 m0, s51
	v_lshl_add_u64 v[234:235], s[14:15], 0, v[156:157]
	ds_read_b128 v[172:175], v196 offset:32768
	ds_read_b128 v[198:201], v196 offset:33792
	ds_read_b128 v[202:205], v196 offset:34816
	ds_read_b128 v[206:209], v196 offset:35840
	ds_read_b128 v[210:213], v196 offset:36864
	ds_read_b128 v[214:217], v196 offset:37888
	ds_read_b128 v[218:221], v196 offset:38912
	ds_read_b128 v[222:225], v196 offset:39936
	global_load_lds_dwordx4 v[234:235], off
	v_lshl_add_u64 v[234:235], s[14:15], 0, v[158:159]
	s_mov_b32 m0, s52
	s_nop 0
	global_load_lds_dwordx4 v[234:235], off
	s_waitcnt vmcnt(8)
	s_waitcnt lgkmcnt(0)
	s_barrier
	s_waitcnt lgkmcnt(0)
	v_mfma_f32_16x16x32_bf16 v[124:127], v[128:131], v[172:175], v[124:127]
	v_mfma_f32_16x16x32_bf16 v[120:123], v[136:139], v[172:175], v[120:123]
	v_mfma_f32_16x16x32_bf16 v[108:111], v[128:131], v[202:205], v[108:111]
	v_mfma_f32_16x16x32_bf16 v[104:107], v[136:139], v[202:205], v[104:107]
	v_mfma_f32_16x16x32_bf16 v[92:95], v[128:131], v[210:213], v[92:95]
	v_mfma_f32_16x16x32_bf16 v[88:91], v[136:139], v[210:213], v[88:91]
	v_mfma_f32_16x16x32_bf16 v[76:79], v[128:131], v[218:221], v[76:79]
	v_mfma_f32_16x16x32_bf16 v[72:75], v[136:139], v[218:221], v[72:75]
	v_mfma_f32_16x16x32_bf16 v[124:127], v[132:135], v[198:201], v[124:127]
	v_mfma_f32_16x16x32_bf16 v[120:123], v[140:143], v[198:201], v[120:123]
	v_mfma_f32_16x16x32_bf16 v[108:111], v[132:135], v[206:209], v[108:111]
	v_mfma_f32_16x16x32_bf16 v[104:107], v[140:143], v[206:209], v[104:107]
	v_mfma_f32_16x16x32_bf16 v[92:95], v[132:135], v[214:217], v[92:95]
	v_mfma_f32_16x16x32_bf16 v[88:91], v[140:143], v[214:217], v[88:91]
	v_mfma_f32_16x16x32_bf16 v[76:79], v[132:135], v[222:225], v[76:79]
	v_mfma_f32_16x16x32_bf16 v[72:75], v[140:143], v[222:225], v[72:75]
	v_mfma_f32_16x16x32_bf16 v[116:119], v[144:147], v[172:175], v[116:119]
	v_mfma_f32_16x16x32_bf16 v[112:115], v[152:155], v[172:175], v[112:115]
	v_mfma_f32_16x16x32_bf16 v[100:103], v[144:147], v[202:205], v[100:103]
	v_mfma_f32_16x16x32_bf16 v[96:99], v[152:155], v[202:205], v[96:99]
	v_mfma_f32_16x16x32_bf16 v[84:87], v[144:147], v[210:213], v[84:87]
	v_mfma_f32_16x16x32_bf16 v[80:83], v[152:155], v[210:213], v[80:83]
	v_mfma_f32_16x16x32_bf16 v[68:71], v[144:147], v[218:221], v[68:71]
	v_mfma_f32_16x16x32_bf16 v[64:67], v[152:155], v[218:221], v[64:67]
	v_mfma_f32_16x16x32_bf16 v[116:119], v[148:151], v[198:201], v[116:119]
	v_mfma_f32_16x16x32_bf16 v[112:115], v[168:171], v[198:201], v[112:115]
	v_mfma_f32_16x16x32_bf16 v[100:103], v[148:151], v[206:209], v[100:103]
	v_mfma_f32_16x16x32_bf16 v[96:99], v[168:171], v[206:209], v[96:99]
	v_mfma_f32_16x16x32_bf16 v[84:87], v[148:151], v[214:217], v[84:87]
	v_mfma_f32_16x16x32_bf16 v[80:83], v[168:171], v[214:217], v[80:83]
	v_mfma_f32_16x16x32_bf16 v[68:71], v[148:151], v[222:225], v[68:71]
	v_mfma_f32_16x16x32_bf16 v[64:67], v[168:171], v[222:225], v[64:67]
	s_barrier
; #define PG8_STAGE(bufoff, gbase, voff) do { _Pragma("unroll") for (int _i = 0; _i < 2; ++_i) \
;         __builtin_amdgcn_global_load_lds((const unsigned*)((const char*)(gbase) + (voff)[_i]), (LAS unsigned*)(lds + (bufoff) + ldsw + _i * 8192), 16, 0, 0); } while (0)
; #define PG8_LDA(dst, b, h) do { _Pragma("unroll") for (int m = 0; m < 4; ++m) _Pragma("unroll") for (int k = 0; k < 2; ++k) dst[m][k] = *(const LAS bf16x8*)(lds + PG8_SA(b, h) + aoff + m * 2048 + k * 1024); } while (0)
; #define PG8_MMA(ai, bj, At, Bt) do { __builtin_amdgcn_s_setprio(1); _Pragma("unroll") for (int m = 0; m < 4; ++m) _Pragma("unroll") for (int n = 0; n < 2; ++n) _Pragma("unroll") for (int k = 0; k < 2; ++k) \
;         acc[ai][bj][m][n] = __builtin_amdgcn_mfma_f32_16x16x32_bf16(Bt[n][k], At[m][k], acc[ai][bj][m][n], 0, 0, 0); __builtin_amdgcn_s_setprio(0); } while (0)
; #define PG8_WAIT_V(n) asm volatile("s_waitcnt vmcnt(" #n ")" ::: "memory")
; #define PG8_WAIT_L(n) asm volatile("s_waitcnt lgkmcnt(" #n ")" ::: "memory")
; #define PG8_BAR __builtin_amdgcn_s_barrier()
; #define PG8_SCHED __builtin_amdgcn_sched_barrier(0)
; template <class Epi, class Sched>
; __device__ __forceinline__ void gemm_phase(LAS unsigned char* lds, const Gemm g, const Sched& S, const Epi& E) {
;     ...
;             PG8_LDA(At, 1, 1); PG8_STAGE(PG8_SB(1, 0), b3, voffB); PG8_STAGE(PG8_SB(1, 1), b3 + hstepB, voffB); PG8_STAGE(PG8_SA(1, 0), a3, voffA);
;             PG8_WAIT_V(8); PG8_WAIT_L(0); PG8_BAR; PG8_MMA(1, 0, At, B0); PG8_MMA(1, 1, At, B1); PG8_BAR; PG8_SCHED;
;         }
	s_add_i32 s0, s0, s20
	v_lshl_add_u64 v[226:227], v[226:227], 0, s[30:31]
	s_mov_b32 m0, s0
	ds_read_b128 v[172:175], v196 offset:49152
	ds_read_b128 v[198:201], v196 offset:50176
	ds_read_b128 v[202:205], v196 offset:51200
	ds_read_b128 v[206:209], v196 offset:52224
	ds_read_b128 v[210:213], v196 offset:53248
	ds_read_b128 v[214:217], v196 offset:54272
	ds_read_b128 v[218:221], v196 offset:55296
	ds_read_b128 v[222:225], v196 offset:56320
	global_load_lds_dwordx4 v[226:227], off
	s_add_i32 m0, s0, 0x2000
	s_add_u32 s6, s6, 0xb0080
	v_lshl_add_u64 v[226:227], v[228:229], 0, s[30:31]
	s_addc_u32 s7, s7, 0
	s_add_i32 s0, s26, s20
	global_load_lds_dwordx4 v[226:227], off
	v_lshl_add_u64 v[226:227], s[6:7], 0, v[160:161]
	s_mov_b32 m0, s0
	s_nop 0
	global_load_lds_dwordx4 v[226:227], off
	v_lshl_add_u64 v[226:227], s[6:7], 0, v[162:163]
	s_add_i32 m0, s0, 0x2000
	s_nop 0
	global_load_lds_dwordx4 v[226:227], off
	v_lshl_add_u64 v[226:227], v[230:231], 0, s[30:31]
	s_mov_b32 m0, s24
	s_nop 0
	global_load_lds_dwordx4 v[226:227], off
	v_lshl_add_u64 v[226:227], v[232:233], 0, s[30:31]
	s_mov_b32 m0, s25
	s_nop 0
	global_load_lds_dwordx4 v[226:227], off
	s_waitcnt vmcnt(8)
	s_waitcnt lgkmcnt(0)
	s_barrier
	s_waitcnt lgkmcnt(0)
	v_mfma_f32_16x16x32_bf16 v[60:63], v[128:131], v[172:175], v[60:63]
	v_mfma_f32_16x16x32_bf16 v[56:59], v[136:139], v[172:175], v[56:59]
	v_mfma_f32_16x16x32_bf16 v[44:47], v[128:131], v[202:205], v[44:47]
	v_mfma_f32_16x16x32_bf16 v[40:43], v[136:139], v[202:205], v[40:43]
	v_mfma_f32_16x16x32_bf16 v[28:31], v[128:131], v[210:213], v[28:31]
	v_mfma_f32_16x16x32_bf16 v[24:27], v[136:139], v[210:213], v[24:27]
	v_mfma_f32_16x16x32_bf16 v[12:15], v[128:131], v[218:221], v[12:15]
	v_mfma_f32_16x16x32_bf16 v[8:11], v[136:139], v[218:221], v[8:11]
	v_mfma_f32_16x16x32_bf16 v[60:63], v[132:135], v[198:201], v[60:63]
	v_mfma_f32_16x16x32_bf16 v[56:59], v[140:143], v[198:201], v[56:59]
	v_mfma_f32_16x16x32_bf16 v[44:47], v[132:135], v[206:209], v[44:47]
	v_mfma_f32_16x16x32_bf16 v[40:43], v[140:143], v[206:209], v[40:43]
	v_mfma_f32_16x16x32_bf16 v[28:31], v[132:135], v[214:217], v[28:31]
	v_mfma_f32_16x16x32_bf16 v[24:27], v[140:143], v[214:217], v[24:27]
	v_mfma_f32_16x16x32_bf16 v[12:15], v[132:135], v[222:225], v[12:15]
	v_mfma_f32_16x16x32_bf16 v[8:11], v[140:143], v[222:225], v[8:11]
	v_mfma_f32_16x16x32_bf16 v[52:55], v[144:147], v[172:175], v[52:55]
	v_mfma_f32_16x16x32_bf16 v[48:51], v[152:155], v[172:175], v[48:51]
	v_mfma_f32_16x16x32_bf16 v[36:39], v[144:147], v[202:205], v[36:39]
	v_mfma_f32_16x16x32_bf16 v[32:35], v[152:155], v[202:205], v[32:35]
	v_mfma_f32_16x16x32_bf16 v[20:23], v[144:147], v[210:213], v[20:23]
	v_mfma_f32_16x16x32_bf16 v[16:19], v[152:155], v[210:213], v[16:19]
	v_mfma_f32_16x16x32_bf16 v[4:7], v[144:147], v[218:221], v[4:7]
	v_mfma_f32_16x16x32_bf16 v[0:3], v[152:155], v[218:221], v[0:3]
	v_mfma_f32_16x16x32_bf16 v[52:55], v[148:151], v[198:201], v[52:55]
	v_mfma_f32_16x16x32_bf16 v[48:51], v[168:171], v[198:201], v[48:51]
	v_mfma_f32_16x16x32_bf16 v[36:39], v[148:151], v[206:209], v[36:39]
	v_mfma_f32_16x16x32_bf16 v[32:35], v[168:171], v[206:209], v[32:35]
	v_mfma_f32_16x16x32_bf16 v[20:23], v[148:151], v[214:217], v[20:23]
	v_mfma_f32_16x16x32_bf16 v[16:19], v[168:171], v[214:217], v[16:19]
	v_mfma_f32_16x16x32_bf16 v[4:7], v[148:151], v[222:225], v[4:7]
	v_mfma_f32_16x16x32_bf16 v[0:3], v[168:171], v[222:225], v[0:3]
	s_barrier
	s_add_i32 s54, s54, 2
	s_add_u32 s33, s33, 0x100
	s_addc_u32 s53, s53, 0
	s_cmp_gt_u32 s54, 41
	s_mov_b64 s[44:45], s[46:47]
